# v73 + nt (streaming) policy on the 64 adaLN GEMV weight loads (w_ada, read once) in P0
# speedup vs baseline: 1.0033x; 1.0001x over previous
; __device__ __forceinline__ float rdlane(float v, int l) { return __int_as_float(__builtin_amdgcn_readlane(__float_as_int(v), l)); }
; __device__ __forceinline__ void p0_prologue(Frame& F) {
;     ...
;                 const float* wp = F.w_ada + (size_t)kbase * NADA + col;
; #pragma unroll 16
;                 for (int kk = 0; kk < 64; ++kk) { const f32x4 w = *(const f32x4*)(wp + (size_t)kk * NADA);
;                     a0 += w * rdlane(s0, kk); a1 += w * rdlane(s1, kk); a2 += w * rdlane(s2, kk); a3 += w * rdlane(s3, kk); }
.LBB0_17:
	v_add_co_u32_e32 v52, vcc, s47, v24
	v_add_co_u32_e64 v54, s[2:3], s49, v24
	s_nop 0
	v_addc_co_u32_e32 v53, vcc, -1, v25, vcc
	global_load_dwordx4 v[66:69], v[52:53], off nt
	v_readlane_b32 s28, v56, s29
	v_readlane_b32 s34, v57, s29
	v_readlane_b32 s64, v63, s29
	v_readlane_b32 s66, v64, s29
	s_add_i32 s36, s29, 1
	s_add_i32 s38, s29, 2
	s_add_i32 s40, s29, 3
	s_add_i32 s52, s29, 4
	s_add_i32 s68, s29, 5
	s_add_i32 s89, s29, 6
	s_add_i32 s88, s29, 7
	s_add_i32 s86, s29, 8
	s_add_i32 s87, s29, 9
	s_add_i32 s78, s29, 10
	s_add_i32 s85, s29, 11
	s_add_i32 s84, s29, 12
	s_add_i32 s83, s29, 13
	s_add_i32 s82, s29, 14
	s_add_i32 s81, s29, 15
	s_add_i32 s29, s29, 16
	v_addc_co_u32_e64 v55, vcc, -1, v25, s[2:3]
	s_mov_b32 s0, 0x18000
	v_add_co_u32_e64 v30, s[16:17], s0, v24
	s_mov_b32 s0, 0x30000
	v_add_co_u32_e64 v32, s[18:19], s0, v24
	s_mov_b32 s0, 0x48000
	v_add_co_u32_e64 v34, s[20:21], s0, v24
	s_mov_b32 s0, 0x60000
	v_add_co_u32_e64 v50, s[4:5], s51, v24
	v_add_co_u32_e64 v38, s[22:23], s0, v24
	s_nop 0
	v_addc_co_u32_e64 v51, vcc, -1, v25, s[4:5]
	v_addc_co_u32_e64 v31, vcc, 0, v25, s[16:17]
	v_addc_co_u32_e64 v33, vcc, 0, v25, s[18:19]
	v_addc_co_u32_e64 v35, vcc, 0, v25, s[20:21]
	v_addc_co_u32_e64 v39, vcc, 0, v25, s[22:23]
	v_readlane_b32 s16, v56, s36
	v_readlane_b32 s18, v57, s36
	v_readlane_b32 s20, v63, s36
	v_readlane_b32 s22, v64, s36
	v_add_co_u32_e64 v46, s[6:7], s53, v24
	v_readlane_b32 s76, v56, s38
	s_nop 0
	v_addc_co_u32_e64 v47, vcc, -1, v25, s[6:7]
	v_readlane_b32 s74, v57, s38
	v_readlane_b32 s72, v63, s38
	v_readlane_b32 s58, v64, s38
	v_add_co_u32_e64 v40, s[8:9], s55, v24
	v_readlane_b32 s56, v56, s40
	s_nop 0
	v_addc_co_u32_e64 v41, vcc, -1, v25, s[8:9]
	v_readlane_b32 s50, v57, s40
	v_readlane_b32 s48, v63, s40
	v_readlane_b32 s46, v64, s40
	v_add_co_u32_e64 v36, s[10:11], s57, v24
	v_readlane_b32 s44, v56, s52
	s_nop 0
	v_addc_co_u32_e64 v37, vcc, -1, v25, s[10:11]
	v_readlane_b32 s42, v57, s52
	v_readlane_b32 s36, v63, s52
	v_readlane_b32 s38, v64, s52
	v_add_co_u32_e64 v28, s[12:13], s59, v24
	v_readlane_b32 s40, v56, s68
	s_nop 0
	v_addc_co_u32_e64 v29, vcc, -1, v25, s[12:13]
	s_waitcnt vmcnt(0)
	v_pk_fma_f32 v[14:15], v[66:67], s[28:29], v[14:15] op_sel_hi:[1,0,1]
	v_pk_fma_f32 v[10:11], v[66:67], s[34:35], v[10:11] op_sel_hi:[1,0,1]
	v_pk_fma_f32 v[6:7], v[66:67], s[64:65], v[6:7] op_sel_hi:[1,0,1]
	v_pk_fma_f32 v[52:53], v[68:69], s[66:67], v[4:5] op_sel_hi:[1,0,1]
	v_pk_fma_f32 v[66:67], v[66:67], s[66:67], v[2:3] op_sel_hi:[1,0,1]
	global_load_dwordx4 v[2:5], v[54:55], off nt
	v_pk_fma_f32 v[16:17], v[68:69], s[28:29], v[16:17] op_sel_hi:[1,0,1]
	v_pk_fma_f32 v[12:13], v[68:69], s[34:35], v[12:13] op_sel_hi:[1,0,1]
	v_pk_fma_f32 v[8:9], v[68:69], s[64:65], v[8:9] op_sel_hi:[1,0,1]
	v_readlane_b32 s54, v57, s68
	v_readlane_b32 s52, v63, s68
	v_readlane_b32 s96, v64, s68
	global_load_dwordx4 v[18:21], v[24:25], off nt
	s_mov_b32 s0, 0x78000
	v_add_co_u32_e64 v42, s[24:25], s0, v24
	s_mov_b32 s0, 0x90000
	v_add_co_u32_e64 v26, s[14:15], s65, v24
	v_add_co_u32_e64 v44, s[0:1], s0, v24
	s_mov_b32 s26, 0xa8000
	v_add_co_u32_e64 v48, s[26:27], s26, v24
	v_addc_co_u32_e64 v27, vcc, -1, v25, s[14:15]
	v_addc_co_u32_e64 v43, vcc, 0, v25, s[24:25]
	v_addc_co_u32_e64 v45, vcc, 0, v25, s[0:1]
	v_readlane_b32 s70, v56, s89
	v_readlane_b32 s68, v57, s89
	v_addc_co_u32_e64 v49, vcc, 0, v25, s[26:27]
	v_readlane_b32 s26, v63, s89
	v_readlane_b32 s4, v64, s89
	v_readlane_b32 s2, v56, s88
	v_readlane_b32 s0, v57, s88
	v_readlane_b32 s8, v63, s88
	v_readlane_b32 s6, v64, s88
	v_readlane_b32 s10, v56, s86
	v_readlane_b32 s12, v57, s86
	v_readlane_b32 s14, v63, s86
	v_readlane_b32 s24, v63, s87
	v_readlane_b32 s28, v56, s78
	v_readlane_b32 s34, v57, s78
	v_readlane_b32 s64, v63, s78
	v_readlane_b32 s66, v64, s78
	v_readlane_b32 s78, v63, s85
	s_cmp_eq_u32 s29, 64
	s_waitcnt vmcnt(1)
	v_pk_fma_f32 v[16:17], v[4:5], s[16:17], v[16:17] op_sel_hi:[1,0,1]
	v_pk_fma_f32 v[14:15], v[2:3], s[16:17], v[14:15] op_sel_hi:[1,0,1]
	v_pk_fma_f32 v[12:13], v[4:5], s[18:19], v[12:13] op_sel_hi:[1,0,1]
	v_pk_fma_f32 v[10:11], v[2:3], s[18:19], v[10:11] op_sel_hi:[1,0,1]
	v_pk_fma_f32 v[8:9], v[4:5], s[20:21], v[8:9] op_sel_hi:[1,0,1]
	v_pk_fma_f32 v[6:7], v[2:3], s[20:21], v[6:7] op_sel_hi:[1,0,1]
	v_pk_fma_f32 v[52:53], v[4:5], s[22:23], v[52:53] op_sel_hi:[1,0,1]
	v_pk_fma_f32 v[54:55], v[2:3], s[22:23], v[66:67] op_sel_hi:[1,0,1]
	global_load_dwordx4 v[2:5], v[50:51], off nt
	v_readlane_b32 s16, v64, s86
	v_readlane_b32 s18, v56, s87
	v_readlane_b32 s20, v57, s87
	v_readlane_b32 s22, v64, s87
	v_readlane_b32 s86, v56, s84
	s_waitcnt vmcnt(0)
	v_pk_fma_f32 v[16:17], v[4:5], s[76:77], v[16:17] op_sel_hi:[1,0,1]
	v_pk_fma_f32 v[14:15], v[2:3], s[76:77], v[14:15] op_sel_hi:[1,0,1]
	v_pk_fma_f32 v[12:13], v[4:5], s[74:75], v[12:13] op_sel_hi:[1,0,1]
	v_pk_fma_f32 v[10:11], v[2:3], s[74:75], v[10:11] op_sel_hi:[1,0,1]
	v_pk_fma_f32 v[8:9], v[4:5], s[72:73], v[8:9] op_sel_hi:[1,0,1]
	v_pk_fma_f32 v[6:7], v[2:3], s[72:73], v[6:7] op_sel_hi:[1,0,1]
	v_pk_fma_f32 v[50:51], v[4:5], s[58:59], v[52:53] op_sel_hi:[1,0,1]
	v_pk_fma_f32 v[52:53], v[2:3], s[58:59], v[54:55] op_sel_hi:[1,0,1]
	global_load_dwordx4 v[2:5], v[46:47], off nt
	v_readlane_b32 s72, v56, s85
	v_readlane_b32 s74, v57, s85
	v_readlane_b32 s76, v64, s85
	v_readlane_b32 s58, v63, s84
	s_waitcnt vmcnt(0)
; __device__ __forceinline__ float rdlane(float v, int l) { return __int_as_float(__builtin_amdgcn_readlane(__float_as_int(v), l)); }
; __device__ __forceinline__ void p0_prologue(Frame& F) {
;     ...
;                 const float* wp = F.w_ada + (size_t)kbase * NADA + col;
; #pragma unroll 16
;                 for (int kk = 0; kk < 64; ++kk) { const f32x4 w = *(const f32x4*)(wp + (size_t)kk * NADA);
;                     a0 += w * rdlane(s0, kk); a1 += w * rdlane(s1, kk); a2 += w * rdlane(s2, kk); a3 += w * rdlane(s3, kk); }
	v_pk_fma_f32 v[16:17], v[4:5], s[56:57], v[16:17] op_sel_hi:[1,0,1]
	v_pk_fma_f32 v[14:15], v[2:3], s[56:57], v[14:15] op_sel_hi:[1,0,1]
	v_pk_fma_f32 v[12:13], v[4:5], s[50:51], v[12:13] op_sel_hi:[1,0,1]
	v_pk_fma_f32 v[10:11], v[2:3], s[50:51], v[10:11] op_sel_hi:[1,0,1]
	v_pk_fma_f32 v[8:9], v[4:5], s[48:49], v[8:9] op_sel_hi:[1,0,1]
	v_pk_fma_f32 v[6:7], v[2:3], s[48:49], v[6:7] op_sel_hi:[1,0,1]
	v_pk_fma_f32 v[46:47], v[4:5], s[46:47], v[50:51] op_sel_hi:[1,0,1]
	v_pk_fma_f32 v[50:51], v[2:3], s[46:47], v[52:53] op_sel_hi:[1,0,1]
	global_load_dwordx4 v[2:5], v[40:41], off nt
	v_readlane_b32 s56, v57, s84
	v_readlane_b32 s46, v56, s82
	v_readlane_b32 s48, v57, s82
	v_readlane_b32 s50, v63, s82
	s_waitcnt vmcnt(0)
	v_pk_fma_f32 v[16:17], v[4:5], s[44:45], v[16:17] op_sel_hi:[1,0,1]
	v_pk_fma_f32 v[14:15], v[2:3], s[44:45], v[14:15] op_sel_hi:[1,0,1]
	v_pk_fma_f32 v[12:13], v[4:5], s[42:43], v[12:13] op_sel_hi:[1,0,1]
	v_pk_fma_f32 v[10:11], v[2:3], s[42:43], v[10:11] op_sel_hi:[1,0,1]
	v_pk_fma_f32 v[8:9], v[4:5], s[36:37], v[8:9] op_sel_hi:[1,0,1]
	v_pk_fma_f32 v[6:7], v[2:3], s[36:37], v[6:7] op_sel_hi:[1,0,1]
	v_pk_fma_f32 v[40:41], v[4:5], s[38:39], v[46:47] op_sel_hi:[1,0,1]
	v_pk_fma_f32 v[46:47], v[2:3], s[38:39], v[50:51] op_sel_hi:[1,0,1]
	global_load_dwordx4 v[2:5], v[36:37], off nt
	v_readlane_b32 s36, v64, s84
	v_readlane_b32 s38, v56, s83
	v_readlane_b32 s44, v63, s83
	v_readlane_b32 s42, v64, s83
	s_waitcnt vmcnt(0)
	v_pk_fma_f32 v[16:17], v[4:5], s[40:41], v[16:17] op_sel_hi:[1,0,1]
	v_pk_fma_f32 v[14:15], v[2:3], s[40:41], v[14:15] op_sel_hi:[1,0,1]
	v_pk_fma_f32 v[12:13], v[4:5], s[54:55], v[12:13] op_sel_hi:[1,0,1]
	v_pk_fma_f32 v[10:11], v[2:3], s[54:55], v[10:11] op_sel_hi:[1,0,1]
	v_pk_fma_f32 v[50:51], v[4:5], s[52:53], v[8:9] op_sel_hi:[1,0,1]
	v_pk_fma_f32 v[52:53], v[2:3], s[52:53], v[6:7] op_sel_hi:[1,0,1]
	v_pk_fma_f32 v[54:55], v[4:5], s[96:97], v[40:41] op_sel_hi:[1,0,1]
	v_pk_fma_f32 v[46:47], v[2:3], s[96:97], v[46:47] op_sel_hi:[1,0,1]
	global_load_dwordx4 v[2:5], v[28:29], off nt
	v_readlane_b32 s40, v57, s83
	v_readlane_b32 s52, v64, s82
	v_readlane_b32 s54, v64, s81
	v_lshl_add_u64 v[24:25], v[24:25], 0, s[60:61]
	s_waitcnt vmcnt(0)
	v_pk_fma_f32 v[66:67], v[4:5], s[70:71], v[16:17] op_sel_hi:[1,0,1]
	v_pk_fma_f32 v[68:69], v[2:3], s[70:71], v[14:15] op_sel_hi:[1,0,1]
	v_pk_fma_f32 v[70:71], v[4:5], s[68:69], v[12:13] op_sel_hi:[1,0,1]
	v_pk_fma_f32 v[72:73], v[2:3], s[68:69], v[10:11] op_sel_hi:[1,0,1]
	global_load_dwordx4 v[6:9], v[26:27], off nt
	global_load_dwordx4 v[10:13], v[30:31], off nt
	global_load_dwordx4 v[14:17], v[32:33], off nt
	s_nop 0
	global_load_dwordx4 v[26:29], v[34:35], off nt
	global_load_dwordx4 v[30:33], v[38:39], off nt
	s_nop 0
	global_load_dwordx4 v[34:37], v[42:43], off nt
	global_load_dwordx4 v[38:41], v[44:45], off nt
	s_nop 0
	global_load_dwordx4 v[42:45], v[48:49], off nt
	v_pk_fma_f32 v[48:49], v[4:5], s[26:27], v[50:51] op_sel_hi:[1,0,1]
	v_pk_fma_f32 v[50:51], v[2:3], s[26:27], v[52:53] op_sel_hi:[1,0,1]
	v_pk_fma_f32 v[4:5], v[4:5], s[4:5], v[54:55] op_sel_hi:[1,0,1]
	v_pk_fma_f32 v[2:3], v[2:3], s[4:5], v[46:47] op_sel_hi:[1,0,1]
	v_readlane_b32 s26, v56, s81
	v_readlane_b32 s4, v57, s81
	s_waitcnt vmcnt(7)
	v_pk_fma_f32 v[46:47], v[8:9], s[2:3], v[66:67] op_sel_hi:[1,0,1]
	v_pk_fma_f32 v[52:53], v[6:7], s[2:3], v[68:69] op_sel_hi:[1,0,1]
	v_pk_fma_f32 v[54:55], v[8:9], s[0:1], v[70:71] op_sel_hi:[1,0,1]
	v_pk_fma_f32 v[66:67], v[6:7], s[0:1], v[72:73] op_sel_hi:[1,0,1]
	v_pk_fma_f32 v[48:49], v[8:9], s[8:9], v[48:49] op_sel_hi:[1,0,1]
	v_pk_fma_f32 v[50:51], v[6:7], s[8:9], v[50:51] op_sel_hi:[1,0,1]
	v_pk_fma_f32 v[4:5], v[8:9], s[6:7], v[4:5] op_sel_hi:[1,0,1]
	v_pk_fma_f32 v[2:3], v[6:7], s[6:7], v[2:3] op_sel_hi:[1,0,1]
	v_pk_fma_f32 v[6:7], v[20:21], s[10:11], v[46:47] op_sel_hi:[1,0,1]
	v_pk_fma_f32 v[8:9], v[18:19], s[10:11], v[52:53] op_sel_hi:[1,0,1]
	v_pk_fma_f32 v[46:47], v[20:21], s[12:13], v[54:55] op_sel_hi:[1,0,1]
	v_pk_fma_f32 v[52:53], v[18:19], s[12:13], v[66:67] op_sel_hi:[1,0,1]
	v_pk_fma_f32 v[48:49], v[20:21], s[14:15], v[48:49] op_sel_hi:[1,0,1]
	v_pk_fma_f32 v[50:51], v[18:19], s[14:15], v[50:51] op_sel_hi:[1,0,1]
	v_pk_fma_f32 v[4:5], v[20:21], s[16:17], v[4:5] op_sel_hi:[1,0,1]
	v_pk_fma_f32 v[2:3], v[18:19], s[16:17], v[2:3] op_sel_hi:[1,0,1]
	s_waitcnt vmcnt(6)
	v_pk_fma_f32 v[6:7], v[12:13], s[18:19], v[6:7] op_sel_hi:[1,0,1]
	v_pk_fma_f32 v[8:9], v[10:11], s[18:19], v[8:9] op_sel_hi:[1,0,1]
	v_pk_fma_f32 v[18:19], v[12:13], s[20:21], v[46:47] op_sel_hi:[1,0,1]
	v_pk_fma_f32 v[20:21], v[10:11], s[20:21], v[52:53] op_sel_hi:[1,0,1]
	v_pk_fma_f32 v[46:47], v[12:13], s[24:25], v[48:49] op_sel_hi:[1,0,1]
	v_pk_fma_f32 v[48:49], v[10:11], s[24:25], v[50:51] op_sel_hi:[1,0,1]
	v_pk_fma_f32 v[4:5], v[12:13], s[22:23], v[4:5] op_sel_hi:[1,0,1]
	v_pk_fma_f32 v[2:3], v[10:11], s[22:23], v[2:3] op_sel_hi:[1,0,1]
	s_waitcnt vmcnt(5)
	v_pk_fma_f32 v[6:7], v[16:17], s[28:29], v[6:7] op_sel_hi:[1,0,1]
	v_pk_fma_f32 v[8:9], v[14:15], s[28:29], v[8:9] op_sel_hi:[1,0,1]
	v_pk_fma_f32 v[10:11], v[16:17], s[34:35], v[18:19] op_sel_hi:[1,0,1]
	v_pk_fma_f32 v[12:13], v[14:15], s[34:35], v[20:21] op_sel_hi:[1,0,1]
	v_pk_fma_f32 v[18:19], v[16:17], s[64:65], v[46:47] op_sel_hi:[1,0,1]
	v_pk_fma_f32 v[20:21], v[14:15], s[64:65], v[48:49] op_sel_hi:[1,0,1]
	v_pk_fma_f32 v[4:5], v[16:17], s[66:67], v[4:5] op_sel_hi:[1,0,1]
	v_pk_fma_f32 v[2:3], v[14:15], s[66:67], v[2:3] op_sel_hi:[1,0,1]
	s_waitcnt vmcnt(4)
; __device__ __forceinline__ float rdlane(float v, int l) { return __int_as_float(__builtin_amdgcn_readlane(__float_as_int(v), l)); }
; __device__ __forceinline__ void p0_prologue(Frame& F) {
;     ...
;                 { const float x0 = F.c[0 * D + kbase + lane], x1 = F.c[1 * D + kbase + lane], x2 = F.c[2 * D + kbase + lane], x3 = F.c[3 * D + kbase + lane];
;                   s0 = x0 / (1.f + expf(-x0)); s1 = x1 / (1.f + expf(-x1)); s2 = x2 / (1.f + expf(-x2)); s3 = x3 / (1.f + expf(-x3)); }
;     ...
;                 for (int kk = 0; kk < 64; ++kk) { const f32x4 w = *(const f32x4*)(wp + (size_t)kk * NADA);
;                     a0 += w * rdlane(s0, kk); a1 += w * rdlane(s1, kk); a2 += w * rdlane(s2, kk); a3 += w * rdlane(s3, kk); }
	v_pk_fma_f32 v[6:7], v[28:29], s[72:73], v[6:7] op_sel_hi:[1,0,1]
	v_pk_fma_f32 v[8:9], v[26:27], s[72:73], v[8:9] op_sel_hi:[1,0,1]
	v_pk_fma_f32 v[10:11], v[28:29], s[74:75], v[10:11] op_sel_hi:[1,0,1]
	v_pk_fma_f32 v[12:13], v[26:27], s[74:75], v[12:13] op_sel_hi:[1,0,1]
	v_pk_fma_f32 v[14:15], v[28:29], s[78:79], v[18:19] op_sel_hi:[1,0,1]
	v_pk_fma_f32 v[16:17], v[26:27], s[78:79], v[20:21] op_sel_hi:[1,0,1]
	v_pk_fma_f32 v[4:5], v[28:29], s[76:77], v[4:5] op_sel_hi:[1,0,1]
	v_pk_fma_f32 v[2:3], v[26:27], s[76:77], v[2:3] op_sel_hi:[1,0,1]
	s_waitcnt vmcnt(3)
	v_pk_fma_f32 v[6:7], v[32:33], s[86:87], v[6:7] op_sel_hi:[1,0,1]
	v_pk_fma_f32 v[8:9], v[30:31], s[86:87], v[8:9] op_sel_hi:[1,0,1]
	v_pk_fma_f32 v[10:11], v[32:33], s[56:57], v[10:11] op_sel_hi:[1,0,1]
	v_pk_fma_f32 v[12:13], v[30:31], s[56:57], v[12:13] op_sel_hi:[1,0,1]
	v_pk_fma_f32 v[14:15], v[32:33], s[58:59], v[14:15] op_sel_hi:[1,0,1]
	v_pk_fma_f32 v[16:17], v[30:31], s[58:59], v[16:17] op_sel_hi:[1,0,1]
	v_pk_fma_f32 v[4:5], v[32:33], s[36:37], v[4:5] op_sel_hi:[1,0,1]
	v_pk_fma_f32 v[2:3], v[30:31], s[36:37], v[2:3] op_sel_hi:[1,0,1]
	s_waitcnt vmcnt(2)
	v_pk_fma_f32 v[6:7], v[36:37], s[38:39], v[6:7] op_sel_hi:[1,0,1]
	v_pk_fma_f32 v[8:9], v[34:35], s[38:39], v[8:9] op_sel_hi:[1,0,1]
	v_pk_fma_f32 v[10:11], v[36:37], s[40:41], v[10:11] op_sel_hi:[1,0,1]
	v_pk_fma_f32 v[12:13], v[34:35], s[40:41], v[12:13] op_sel_hi:[1,0,1]
	v_pk_fma_f32 v[14:15], v[36:37], s[44:45], v[14:15] op_sel_hi:[1,0,1]
	v_pk_fma_f32 v[16:17], v[34:35], s[44:45], v[16:17] op_sel_hi:[1,0,1]
	v_pk_fma_f32 v[4:5], v[36:37], s[42:43], v[4:5] op_sel_hi:[1,0,1]
	v_pk_fma_f32 v[2:3], v[34:35], s[42:43], v[2:3] op_sel_hi:[1,0,1]
	v_readlane_b32 s2, v63, s81
	s_waitcnt vmcnt(1)
	v_pk_fma_f32 v[6:7], v[40:41], s[46:47], v[6:7] op_sel_hi:[1,0,1]
	v_pk_fma_f32 v[8:9], v[38:39], s[46:47], v[8:9] op_sel_hi:[1,0,1]
	v_pk_fma_f32 v[10:11], v[40:41], s[48:49], v[10:11] op_sel_hi:[1,0,1]
	v_pk_fma_f32 v[18:19], v[38:39], s[48:49], v[12:13] op_sel_hi:[1,0,1]
	v_pk_fma_f32 v[20:21], v[40:41], s[50:51], v[14:15] op_sel_hi:[1,0,1]
	v_pk_fma_f32 v[26:27], v[38:39], s[50:51], v[16:17] op_sel_hi:[1,0,1]
	v_pk_fma_f32 v[4:5], v[40:41], s[52:53], v[4:5] op_sel_hi:[1,0,1]
	v_pk_fma_f32 v[2:3], v[38:39], s[52:53], v[2:3] op_sel_hi:[1,0,1]
	s_waitcnt vmcnt(0)
	v_pk_fma_f32 v[16:17], v[44:45], s[26:27], v[6:7] op_sel_hi:[1,0,1]
	v_pk_fma_f32 v[14:15], v[42:43], s[26:27], v[8:9] op_sel_hi:[1,0,1]
	v_pk_fma_f32 v[12:13], v[44:45], s[4:5], v[10:11] op_sel_hi:[1,0,1]
	v_pk_fma_f32 v[10:11], v[42:43], s[4:5], v[18:19] op_sel_hi:[1,0,1]
	v_pk_fma_f32 v[8:9], v[44:45], s[2:3], v[20:21] op_sel_hi:[1,0,1]
	v_pk_fma_f32 v[6:7], v[42:43], s[2:3], v[26:27] op_sel_hi:[1,0,1]
	v_pk_fma_f32 v[4:5], v[44:45], s[54:55], v[4:5] op_sel_hi:[1,0,1]
	v_pk_fma_f32 v[2:3], v[42:43], s[54:55], v[2:3] op_sel_hi:[1,0,1]
	s_cbranch_scc0 .LBB0_17
	v_readlane_b32 s4, v245, 29
	v_lshl_add_u64 v[18:19], s[62:63], 0, v[186:187]
	v_readlane_b32 s6, v245, 31
	v_readlane_b32 s7, v245, 32
	s_or_b32 s0, s62, 64
	v_add_u32_e32 v20, s0, v59
	v_lshl_add_u64 v[24:25], v[18:19], 2, s[6:7]
	global_load_dword v28, v[24:25], off offset:256
	v_add_u32_e32 v18, s0, v58
	v_ashrrev_i32_e32 v19, 31, v18
	v_ashrrev_i32_e32 v21, 31, v20
	v_add_u32_e32 v26, s0, v60
	v_lshl_add_u64 v[18:19], v[18:19], 2, s[6:7]
	v_lshl_add_u64 v[20:21], v[20:21], 2, s[6:7]
	v_ashrrev_i32_e32 v27, 31, v26
	v_lshl_add_u64 v[26:27], v[26:27], 2, s[6:7]
	global_load_dword v18, v[18:19], off
	s_nop 0
	global_load_dword v19, v[20:21], off
	s_nop 0
	global_load_dword v20, v[26:27], off
	s_mov_b32 s63, 0
	v_readlane_b32 s5, v245, 30
	v_readlane_b32 s8, v245, 33
	v_readlane_b32 s9, v245, 34
	v_readlane_b32 s10, v245, 35
	v_readlane_b32 s11, v245, 36
	v_readlane_b32 s12, v245, 37
	v_readlane_b32 s13, v245, 38
	v_readlane_b32 s14, v245, 39
	v_readlane_b32 s15, v245, 40
	v_readlane_b32 s16, v245, 41
	v_readlane_b32 s17, v245, 42
	v_readlane_b32 s18, v245, 43
	v_readlane_b32 s19, v245, 44
	s_waitcnt vmcnt(3)
	v_mul_f32_e32 v21, 0xbfb8aa3b, v28
	v_fma_f32 v26, v28, s41, -v21
	v_rndne_f32_e32 v27, v21
	v_fmac_f32_e32 v26, 0xb2a5705f, v28
	v_sub_f32_e32 v21, v21, v27
	v_add_f32_e32 v21, v21, v26
	v_cvt_i32_f32_e32 v27, v27
	s_waitcnt vmcnt(2)
	v_mul_f32_e32 v29, 0xbfb8aa3b, v18
	s_waitcnt vmcnt(1)
	v_mul_f32_e32 v30, 0xbfb8aa3b, v19
	s_waitcnt vmcnt(0)
; __device__ __forceinline__ float rdlane(float v, int l) { return __int_as_float(__builtin_amdgcn_readlane(__float_as_int(v), l)); }
; __device__ __forceinline__ void p0_prologue(Frame& F) {
;     ...
;                   s0 = x0 / (1.f + expf(-x0)); s1 = x1 / (1.f + expf(-x1)); s2 = x2 / (1.f + expf(-x2)); s3 = x3 / (1.f + expf(-x3)); }
;                 const float* wp = F.w_ada + (size_t)kbase * NADA + col;
; #pragma unroll 16
;                 for (int kk = 0; kk < 64; ++kk) { const f32x4 w = *(const f32x4*)(wp + (size_t)kk * NADA);
;                     a0 += w * rdlane(s0, kk); a1 += w * rdlane(s1, kk); a2 += w * rdlane(s2, kk); a3 += w * rdlane(s3, kk); }
	v_mul_f32_e32 v31, 0xbfb8aa3b, v20
	v_exp_f32_e32 v21, v21
	v_fma_f32 v26, v18, s41, -v29
	v_rndne_f32_e32 v32, v29
	v_fma_f32 v33, v19, s41, -v30
	v_rndne_f32_e32 v34, v30
	v_fma_f32 v35, v20, s41, -v31
	v_rndne_f32_e32 v36, v31
	v_fmac_f32_e32 v26, 0xb2a5705f, v18
	v_sub_f32_e32 v29, v29, v32
	v_fmac_f32_e32 v33, 0xb2a5705f, v19
	v_sub_f32_e32 v30, v30, v34
	v_fmac_f32_e32 v35, 0xb2a5705f, v20
	v_sub_f32_e32 v31, v31, v36
	v_add_f32_e32 v26, v29, v26
	v_add_f32_e32 v29, v30, v33
	v_add_f32_e32 v30, v31, v35
	v_cvt_i32_f32_e32 v32, v32
	v_cvt_i32_f32_e32 v34, v34
	v_cvt_i32_f32_e32 v36, v36
	v_exp_f32_e32 v26, v26
	v_exp_f32_e32 v29, v29
	v_exp_f32_e32 v30, v30
	v_ldexp_f32 v21, v21, v27
	v_cmp_nlt_f32_e32 vcc, s43, v28
	v_ldexp_f32 v26, v26, v32
	v_ldexp_f32 v27, v29, v34
	v_cndmask_b32_e32 v21, 0, v21, vcc
	v_cmp_ngt_f32_e32 vcc, s45, v28
	v_ldexp_f32 v29, v30, v36
	s_nop 0
	v_cndmask_b32_e32 v21, v61, v21, vcc
	v_add_f32_e32 v21, 1.0, v21
	v_cmp_nlt_f32_e32 vcc, s43, v18
	v_div_scale_f32 v30, s[0:1], v21, v21, v28
	s_nop 0
	v_cndmask_b32_e32 v26, 0, v26, vcc
	v_cmp_ngt_f32_e64 s[0:1], s45, v18
	v_cmp_nlt_f32_e32 vcc, s43, v19
	v_rcp_f32_e32 v32, v30
	v_cndmask_b32_e64 v26, v61, v26, s[0:1]
	v_cndmask_b32_e32 v27, 0, v27, vcc
	v_cmp_ngt_f32_e64 s[0:1], s45, v19
	v_add_f32_e32 v26, 1.0, v26
	v_cmp_nlt_f32_e32 vcc, s43, v20
	v_cndmask_b32_e64 v27, v61, v27, s[0:1]
	v_div_scale_f32 v33, s[0:1], v26, v26, v18
	v_rcp_f32_e32 v37, v33
	v_fma_f32 v39, -v30, v32, 1.0
	v_cndmask_b32_e32 v29, 0, v29, vcc
	v_div_scale_f32 v31, vcc, v28, v21, v28
	v_fmac_f32_e32 v32, v39, v32
	v_mul_f32_e32 v39, v31, v32
	v_fma_f32 v40, -v33, v37, 1.0
	v_add_f32_e32 v27, 1.0, v27
	v_div_scale_f32 v34, s[0:1], v18, v26, v18
	v_fma_f32 v42, -v30, v39, v31
	v_fmac_f32_e32 v37, v40, v37
	v_div_scale_f32 v35, s[2:3], v27, v27, v19
	v_fmac_f32_e32 v39, v42, v32
	v_mul_f32_e32 v40, v34, v37
	v_rcp_f32_e32 v38, v35
	v_fma_f32 v30, -v30, v39, v31
	v_fma_f32 v31, -v33, v40, v34
	v_div_fmas_f32 v30, v30, v32, v39
	v_fmac_f32_e32 v40, v31, v37
	v_div_fixup_f32 v63, v30, v21, v28
	v_fma_f32 v21, -v33, v40, v34
	s_mov_b64 vcc, s[0:1]
	v_div_fmas_f32 v21, v21, v37, v40
	v_cmp_ngt_f32_e32 vcc, s45, v20
	v_fma_f32 v41, -v35, v38, 1.0
	v_div_fixup_f32 v64, v21, v26, v18
	v_cndmask_b32_e32 v18, v61, v29, vcc
	v_div_scale_f32 v36, s[2:3], v19, v27, v19
	v_fmac_f32_e32 v38, v41, v38
	v_add_f32_e32 v18, 1.0, v18
	v_mul_f32_e32 v41, v36, v38
	v_div_scale_f32 v21, s[0:1], v18, v18, v20
	v_fma_f32 v42, -v35, v41, v36
	v_rcp_f32_e32 v26, v21
	v_fmac_f32_e32 v41, v42, v38
	v_fma_f32 v28, -v35, v41, v36
	s_mov_b64 vcc, s[2:3]
	v_div_fmas_f32 v28, v28, v38, v41
	v_div_fixup_f32 v65, v28, v27, v19
	v_fma_f32 v19, -v21, v26, 1.0
	v_fmac_f32_e32 v26, v19, v26
	v_div_scale_f32 v19, vcc, v20, v18, v20
	v_mul_f32_e32 v27, v19, v26
	v_fma_f32 v28, -v21, v27, v19
	v_fmac_f32_e32 v27, v28, v26
	v_fma_f32 v19, -v21, v27, v19
	v_readlane_b32 s0, v245, 63
	v_div_fmas_f32 v19, v19, v26, v27
	v_readlane_b32 s1, v244, 0
	v_div_fixup_f32 v66, v19, v18, v20
	s_nop 0
	v_lshl_add_u64 v[26:27], s[0:1], 0, v[22:23]
.LBB0_19:
	v_add_co_u32_e32 v54, vcc, 0xffe98000, v26
	v_add_co_u32_e64 v56, s[2:3], s67, v26
	s_nop 0
	v_addc_co_u32_e32 v55, vcc, -1, v27, vcc
	global_load_dwordx4 v[68:71], v[54:55], off nt
	v_readlane_b32 s64, v63, s63
	v_readlane_b32 s34, v64, s63
	v_readlane_b32 s96, v65, s63
	v_readlane_b32 s86, v66, s63
	s_add_i32 s87, s63, 7
	v_addc_co_u32_e64 v57, s[0:1], -1, v27, s[2:3]
	s_add_i32 s36, s63, 1
	v_add_co_u32_e64 v52, s[4:5], s69, v26
	v_add_co_u32_e64 v30, s[16:17], s49, v26
	v_add_co_u32_e64 v34, s[18:19], s51, v26
	v_add_co_u32_e64 v36, s[20:21], s53, v26
	v_add_co_u32_e64 v40, s[22:23], s55, v26
	v_addc_co_u32_e64 v53, s[0:1], -1, v27, s[4:5]
	v_addc_co_u32_e64 v31, s[0:1], -1, v27, s[16:17]
	v_addc_co_u32_e64 v35, s[0:1], -1, v27, s[18:19]
	v_addc_co_u32_e64 v37, s[0:1], -1, v27, s[20:21]
	v_addc_co_u32_e64 v41, s[0:1], -1, v27, s[22:23]
	v_readlane_b32 s16, v63, s36
	v_readlane_b32 s18, v64, s36
	v_readlane_b32 s20, v65, s36
	v_readlane_b32 s22, v66, s36
	s_add_i32 s38, s63, 2
	v_add_co_u32_e64 v48, s[6:7], s71, v26
	v_add_co_u32_e64 v46, s[26:27], s59, v26
	v_add_co_u32_e64 v50, s[28:29], s65, v26
	v_addc_co_u32_e64 v49, s[0:1], -1, v27, s[6:7]
	v_addc_co_u32_e64 v47, s[0:1], -1, v27, s[26:27]
	v_addc_co_u32_e64 v51, s[0:1], -1, v27, s[28:29]
	v_readlane_b32 s26, v63, s38
	v_readlane_b32 s28, v64, s38
	v_readlane_b32 s52, v65, s38
	v_readlane_b32 s50, v66, s38
	s_add_i32 s44, s63, 3
	v_add_co_u32_e64 v44, s[8:9], s73, v26
	v_readlane_b32 s38, v63, s44
	s_nop 0
	v_addc_co_u32_e64 v45, s[0:1], -1, v27, s[8:9]
	v_readlane_b32 s40, v64, s44
	v_readlane_b32 s42, v65, s44
	v_readlane_b32 s44, v66, s44
	s_add_i32 s54, s63, 4
	v_add_co_u32_e64 v38, s[10:11], s75, v26
	v_readlane_b32 s46, v63, s54
	s_nop 0
	v_addc_co_u32_e64 v39, s[0:1], -1, v27, s[10:11]
	v_readlane_b32 s48, v64, s54
	v_readlane_b32 s56, v65, s54
	v_readlane_b32 s58, v66, s54
	s_add_i32 s70, s63, 5
	v_add_co_u32_e64 v32, s[12:13], s77, v26
	v_readlane_b32 s74, v63, s70
	s_nop 0
	v_addc_co_u32_e64 v33, s[0:1], -1, v27, s[12:13]
	v_readlane_b32 s66, v64, s70
	v_readlane_b32 s68, v65, s70
	v_readlane_b32 s70, v66, s70
	global_load_dwordx4 v[18:21], v[26:27], off nt
	s_add_i32 s84, s63, 6
	v_add_co_u32_e64 v28, s[14:15], s47, v26
	s_waitcnt vmcnt(1)
; __device__ __forceinline__ float rdlane(float v, int l) { return __int_as_float(__builtin_amdgcn_readlane(__float_as_int(v), l)); }
; __device__ __forceinline__ void p0_prologue(Frame& F) {
;     ...
;                 for (int kk = 0; kk < 64; ++kk) { const f32x4 w = *(const f32x4*)(wp + (size_t)kk * NADA);
;                     a0 += w * rdlane(s0, kk); a1 += w * rdlane(s1, kk); a2 += w * rdlane(s2, kk); a3 += w * rdlane(s3, kk); }
	v_pk_fma_f32 v[14:15], v[68:69], s[64:65], v[14:15] op_sel_hi:[1,0,1]
	v_pk_fma_f32 v[10:11], v[68:69], s[34:35], v[10:11] op_sel_hi:[1,0,1]
	v_pk_fma_f32 v[6:7], v[68:69], s[96:97], v[6:7] op_sel_hi:[1,0,1]
	v_pk_fma_f32 v[54:55], v[70:71], s[86:87], v[4:5] op_sel_hi:[1,0,1]
	v_pk_fma_f32 v[68:69], v[68:69], s[86:87], v[2:3] op_sel_hi:[1,0,1]
	global_load_dwordx4 v[2:5], v[56:57], off nt
	v_pk_fma_f32 v[16:17], v[70:71], s[64:65], v[16:17] op_sel_hi:[1,0,1]
	v_pk_fma_f32 v[12:13], v[70:71], s[34:35], v[12:13] op_sel_hi:[1,0,1]
	v_pk_fma_f32 v[8:9], v[70:71], s[96:97], v[8:9] op_sel_hi:[1,0,1]
	v_add_co_u32_e64 v42, s[24:25], s57, v26
	v_addc_co_u32_e64 v29, s[0:1], -1, v27, s[14:15]
	s_nop 0
	v_addc_co_u32_e64 v43, s[0:1], -1, v27, s[24:25]
	v_readlane_b32 s72, v63, s84
	v_readlane_b32 s76, v64, s84
	v_readlane_b32 s36, v65, s84
	v_readlane_b32 s24, v66, s84
	s_add_i32 s88, s63, 8
	v_readlane_b32 s10, v63, s87
	v_readlane_b32 s0, v64, s87
	v_readlane_b32 s2, v65, s87
	v_readlane_b32 s4, v66, s87
	s_add_i32 s90, s63, 9
	v_readlane_b32 s6, v63, s88
	v_readlane_b32 s8, v64, s88
	v_readlane_b32 s14, v65, s88
	v_readlane_b32 s12, v66, s88
	s_add_i32 s89, s63, 10
	s_add_i32 s85, s63, 11
	v_readlane_b32 s34, v66, s89
	s_add_i32 s83, s63, 12
	v_readlane_b32 s54, v63, s85
	s_add_i32 s82, s63, 13
	s_add_i32 s81, s63, 14
	v_readlane_b32 s64, v65, s82
	s_add_i32 s78, s63, 15
	s_add_i32 s63, s63, 16
	s_cmp_lg_u32 s63, 64
	s_waitcnt vmcnt(0)
	v_pk_fma_f32 v[16:17], v[4:5], s[16:17], v[16:17] op_sel_hi:[1,0,1]
	v_pk_fma_f32 v[14:15], v[2:3], s[16:17], v[14:15] op_sel_hi:[1,0,1]
	v_pk_fma_f32 v[12:13], v[4:5], s[18:19], v[12:13] op_sel_hi:[1,0,1]
	v_pk_fma_f32 v[10:11], v[2:3], s[18:19], v[10:11] op_sel_hi:[1,0,1]
	v_pk_fma_f32 v[8:9], v[4:5], s[20:21], v[8:9] op_sel_hi:[1,0,1]
	v_pk_fma_f32 v[6:7], v[2:3], s[20:21], v[6:7] op_sel_hi:[1,0,1]
	v_pk_fma_f32 v[54:55], v[4:5], s[22:23], v[54:55] op_sel_hi:[1,0,1]
	v_pk_fma_f32 v[56:57], v[2:3], s[22:23], v[68:69] op_sel_hi:[1,0,1]
	global_load_dwordx4 v[2:5], v[52:53], off nt
	v_readlane_b32 s16, v63, s90
	v_readlane_b32 s18, v64, s90
	v_readlane_b32 s20, v65, s90
	v_readlane_b32 s22, v66, s90
	s_waitcnt vmcnt(0)
	v_pk_fma_f32 v[16:17], v[4:5], s[26:27], v[16:17] op_sel_hi:[1,0,1]
	v_pk_fma_f32 v[14:15], v[2:3], s[26:27], v[14:15] op_sel_hi:[1,0,1]
	v_pk_fma_f32 v[12:13], v[4:5], s[28:29], v[12:13] op_sel_hi:[1,0,1]
	v_pk_fma_f32 v[10:11], v[2:3], s[28:29], v[10:11] op_sel_hi:[1,0,1]
	v_pk_fma_f32 v[8:9], v[4:5], s[52:53], v[8:9] op_sel_hi:[1,0,1]
	v_pk_fma_f32 v[6:7], v[2:3], s[52:53], v[6:7] op_sel_hi:[1,0,1]
	v_pk_fma_f32 v[52:53], v[4:5], s[50:51], v[54:55] op_sel_hi:[1,0,1]
	v_pk_fma_f32 v[54:55], v[2:3], s[50:51], v[56:57] op_sel_hi:[1,0,1]
	global_load_dwordx4 v[2:5], v[48:49], off nt
	v_readlane_b32 s26, v63, s89
	v_readlane_b32 s28, v64, s89
	v_readlane_b32 s52, v65, s89
	v_readlane_b32 s50, v65, s83
	s_waitcnt vmcnt(0)
	v_pk_fma_f32 v[16:17], v[4:5], s[38:39], v[16:17] op_sel_hi:[1,0,1]
	v_pk_fma_f32 v[14:15], v[2:3], s[38:39], v[14:15] op_sel_hi:[1,0,1]
	v_pk_fma_f32 v[12:13], v[4:5], s[40:41], v[12:13] op_sel_hi:[1,0,1]
	v_pk_fma_f32 v[10:11], v[2:3], s[40:41], v[10:11] op_sel_hi:[1,0,1]
	v_pk_fma_f32 v[8:9], v[4:5], s[42:43], v[8:9] op_sel_hi:[1,0,1]
	v_pk_fma_f32 v[6:7], v[2:3], s[42:43], v[6:7] op_sel_hi:[1,0,1]
	v_pk_fma_f32 v[48:49], v[4:5], s[44:45], v[52:53] op_sel_hi:[1,0,1]
	v_pk_fma_f32 v[52:53], v[2:3], s[44:45], v[54:55] op_sel_hi:[1,0,1]
	global_load_dwordx4 v[2:5], v[44:45], off nt
	v_readlane_b32 s38, v64, s85
	v_readlane_b32 s40, v65, s85
	v_readlane_b32 s42, v66, s85
	v_readlane_b32 s44, v63, s83
	s_waitcnt vmcnt(0)
	v_pk_fma_f32 v[16:17], v[4:5], s[46:47], v[16:17] op_sel_hi:[1,0,1]
	v_pk_fma_f32 v[14:15], v[2:3], s[46:47], v[14:15] op_sel_hi:[1,0,1]
	v_pk_fma_f32 v[12:13], v[4:5], s[48:49], v[12:13] op_sel_hi:[1,0,1]
	v_pk_fma_f32 v[10:11], v[2:3], s[48:49], v[10:11] op_sel_hi:[1,0,1]
	v_pk_fma_f32 v[8:9], v[4:5], s[56:57], v[8:9] op_sel_hi:[1,0,1]
	v_pk_fma_f32 v[6:7], v[2:3], s[56:57], v[6:7] op_sel_hi:[1,0,1]
	v_pk_fma_f32 v[44:45], v[4:5], s[58:59], v[48:49] op_sel_hi:[1,0,1]
	v_pk_fma_f32 v[48:49], v[2:3], s[58:59], v[52:53] op_sel_hi:[1,0,1]
	global_load_dwordx4 v[2:5], v[38:39], off nt
	v_readlane_b32 s46, v64, s83
	v_readlane_b32 s48, v66, s83
	v_readlane_b32 s56, v63, s82
	v_readlane_b32 s58, v64, s82
	s_waitcnt vmcnt(0)
	v_pk_fma_f32 v[16:17], v[4:5], s[74:75], v[16:17] op_sel_hi:[1,0,1]
	v_pk_fma_f32 v[14:15], v[2:3], s[74:75], v[14:15] op_sel_hi:[1,0,1]
	v_pk_fma_f32 v[12:13], v[4:5], s[66:67], v[12:13] op_sel_hi:[1,0,1]
	v_pk_fma_f32 v[10:11], v[2:3], s[66:67], v[10:11] op_sel_hi:[1,0,1]
	v_pk_fma_f32 v[52:53], v[4:5], s[68:69], v[8:9] op_sel_hi:[1,0,1]
	v_pk_fma_f32 v[54:55], v[2:3], s[68:69], v[6:7] op_sel_hi:[1,0,1]
	v_pk_fma_f32 v[56:57], v[4:5], s[70:71], v[44:45] op_sel_hi:[1,0,1]
	v_pk_fma_f32 v[48:49], v[2:3], s[70:71], v[48:49] op_sel_hi:[1,0,1]
	global_load_dwordx4 v[2:5], v[32:33], off nt
	v_readlane_b32 s66, v66, s82
	v_readlane_b32 s68, v63, s81
	v_readlane_b32 s70, v64, s81
	v_readlane_b32 s74, v65, s81
	v_lshl_add_u64 v[26:27], v[26:27], 0, s[60:61]
	s_waitcnt vmcnt(0)
; __device__ __forceinline__ float rdlane(float v, int l) { return __int_as_float(__builtin_amdgcn_readlane(__float_as_int(v), l)); }
; __device__ __forceinline__ void p0_prologue(Frame& F) {
;     ...
;                 for (int kk = 0; kk < 64; ++kk) { const f32x4 w = *(const f32x4*)(wp + (size_t)kk * NADA);
;                     a0 += w * rdlane(s0, kk); a1 += w * rdlane(s1, kk); a2 += w * rdlane(s2, kk); a3 += w * rdlane(s3, kk); }
	v_pk_fma_f32 v[68:69], v[4:5], s[72:73], v[16:17] op_sel_hi:[1,0,1]
	v_pk_fma_f32 v[70:71], v[2:3], s[72:73], v[14:15] op_sel_hi:[1,0,1]
	v_pk_fma_f32 v[72:73], v[4:5], s[76:77], v[12:13] op_sel_hi:[1,0,1]
	v_pk_fma_f32 v[74:75], v[2:3], s[76:77], v[10:11] op_sel_hi:[1,0,1]
	global_load_dwordx4 v[6:9], v[28:29], off nt
	global_load_dwordx4 v[10:13], v[30:31], off nt
	global_load_dwordx4 v[14:17], v[34:35], off nt
	s_nop 0
	global_load_dwordx4 v[28:31], v[36:37], off nt
	global_load_dwordx4 v[32:35], v[40:41], off nt
	s_nop 0
	global_load_dwordx4 v[36:39], v[42:43], off nt
	s_nop 0
	global_load_dwordx4 v[40:43], v[46:47], off nt
	s_nop 0
	global_load_dwordx4 v[44:47], v[50:51], off nt
	v_pk_fma_f32 v[50:51], v[4:5], s[36:37], v[52:53] op_sel_hi:[1,0,1]
	v_pk_fma_f32 v[52:53], v[2:3], s[36:37], v[54:55] op_sel_hi:[1,0,1]
	v_pk_fma_f32 v[4:5], v[4:5], s[24:25], v[56:57] op_sel_hi:[1,0,1]
	v_pk_fma_f32 v[2:3], v[2:3], s[24:25], v[48:49] op_sel_hi:[1,0,1]
	v_readlane_b32 s72, v66, s81
	v_readlane_b32 s76, v63, s78
	v_readlane_b32 s36, v64, s78
	v_readlane_b32 s24, v65, s78
	s_waitcnt vmcnt(7)
	v_pk_fma_f32 v[48:49], v[8:9], s[10:11], v[68:69] op_sel_hi:[1,0,1]
	v_pk_fma_f32 v[54:55], v[6:7], s[10:11], v[70:71] op_sel_hi:[1,0,1]
	v_pk_fma_f32 v[56:57], v[8:9], s[0:1], v[72:73] op_sel_hi:[1,0,1]
	v_pk_fma_f32 v[68:69], v[6:7], s[0:1], v[74:75] op_sel_hi:[1,0,1]
	v_pk_fma_f32 v[50:51], v[8:9], s[2:3], v[50:51] op_sel_hi:[1,0,1]
	v_pk_fma_f32 v[52:53], v[6:7], s[2:3], v[52:53] op_sel_hi:[1,0,1]
	v_pk_fma_f32 v[4:5], v[8:9], s[4:5], v[4:5] op_sel_hi:[1,0,1]
	v_pk_fma_f32 v[2:3], v[6:7], s[4:5], v[2:3] op_sel_hi:[1,0,1]
	s_waitcnt vmcnt(6)
	v_pk_fma_f32 v[6:7], v[12:13], s[6:7], v[48:49] op_sel_hi:[1,0,1]
	v_pk_fma_f32 v[8:9], v[10:11], s[6:7], v[54:55] op_sel_hi:[1,0,1]
	v_pk_fma_f32 v[48:49], v[12:13], s[8:9], v[56:57] op_sel_hi:[1,0,1]
	v_pk_fma_f32 v[54:55], v[10:11], s[8:9], v[68:69] op_sel_hi:[1,0,1]
	v_pk_fma_f32 v[50:51], v[12:13], s[14:15], v[50:51] op_sel_hi:[1,0,1]
	v_pk_fma_f32 v[52:53], v[10:11], s[14:15], v[52:53] op_sel_hi:[1,0,1]
	v_pk_fma_f32 v[4:5], v[12:13], s[12:13], v[4:5] op_sel_hi:[1,0,1]
	v_pk_fma_f32 v[2:3], v[10:11], s[12:13], v[2:3] op_sel_hi:[1,0,1]
	s_waitcnt vmcnt(5)
	v_pk_fma_f32 v[6:7], v[16:17], s[16:17], v[6:7] op_sel_hi:[1,0,1]
	v_pk_fma_f32 v[8:9], v[14:15], s[16:17], v[8:9] op_sel_hi:[1,0,1]
	v_pk_fma_f32 v[10:11], v[16:17], s[18:19], v[48:49] op_sel_hi:[1,0,1]
	v_pk_fma_f32 v[12:13], v[14:15], s[18:19], v[54:55] op_sel_hi:[1,0,1]
	v_pk_fma_f32 v[48:49], v[16:17], s[20:21], v[50:51] op_sel_hi:[1,0,1]
	v_pk_fma_f32 v[50:51], v[14:15], s[20:21], v[52:53] op_sel_hi:[1,0,1]
	v_pk_fma_f32 v[4:5], v[16:17], s[22:23], v[4:5] op_sel_hi:[1,0,1]
	v_pk_fma_f32 v[2:3], v[14:15], s[22:23], v[2:3] op_sel_hi:[1,0,1]
	s_waitcnt vmcnt(4)
	v_pk_fma_f32 v[6:7], v[30:31], s[26:27], v[6:7] op_sel_hi:[1,0,1]
	v_pk_fma_f32 v[8:9], v[28:29], s[26:27], v[8:9] op_sel_hi:[1,0,1]
	v_pk_fma_f32 v[10:11], v[30:31], s[28:29], v[10:11] op_sel_hi:[1,0,1]
	v_pk_fma_f32 v[12:13], v[28:29], s[28:29], v[12:13] op_sel_hi:[1,0,1]
	v_pk_fma_f32 v[14:15], v[30:31], s[52:53], v[48:49] op_sel_hi:[1,0,1]
	v_pk_fma_f32 v[16:17], v[28:29], s[52:53], v[50:51] op_sel_hi:[1,0,1]
	v_pk_fma_f32 v[4:5], v[30:31], s[34:35], v[4:5] op_sel_hi:[1,0,1]
	v_pk_fma_f32 v[2:3], v[28:29], s[34:35], v[2:3] op_sel_hi:[1,0,1]
	s_waitcnt vmcnt(3)
	v_pk_fma_f32 v[6:7], v[34:35], s[54:55], v[6:7] op_sel_hi:[1,0,1]
	v_pk_fma_f32 v[8:9], v[32:33], s[54:55], v[8:9] op_sel_hi:[1,0,1]
	v_pk_fma_f32 v[10:11], v[34:35], s[38:39], v[10:11] op_sel_hi:[1,0,1]
	v_pk_fma_f32 v[12:13], v[32:33], s[38:39], v[12:13] op_sel_hi:[1,0,1]
	v_pk_fma_f32 v[14:15], v[34:35], s[40:41], v[14:15] op_sel_hi:[1,0,1]
	v_pk_fma_f32 v[16:17], v[32:33], s[40:41], v[16:17] op_sel_hi:[1,0,1]
	v_pk_fma_f32 v[4:5], v[34:35], s[42:43], v[4:5] op_sel_hi:[1,0,1]
	v_pk_fma_f32 v[2:3], v[32:33], s[42:43], v[2:3] op_sel_hi:[1,0,1]
	s_waitcnt vmcnt(2)
	v_pk_fma_f32 v[6:7], v[38:39], s[44:45], v[6:7] op_sel_hi:[1,0,1]
	v_pk_fma_f32 v[8:9], v[36:37], s[44:45], v[8:9] op_sel_hi:[1,0,1]
	v_pk_fma_f32 v[10:11], v[38:39], s[46:47], v[10:11] op_sel_hi:[1,0,1]
	v_pk_fma_f32 v[12:13], v[36:37], s[46:47], v[12:13] op_sel_hi:[1,0,1]
	v_pk_fma_f32 v[14:15], v[38:39], s[50:51], v[14:15] op_sel_hi:[1,0,1]
	v_pk_fma_f32 v[16:17], v[36:37], s[50:51], v[16:17] op_sel_hi:[1,0,1]
	v_pk_fma_f32 v[4:5], v[38:39], s[48:49], v[4:5] op_sel_hi:[1,0,1]
	v_pk_fma_f32 v[2:3], v[36:37], s[48:49], v[2:3] op_sel_hi:[1,0,1]
	s_waitcnt vmcnt(1)
	v_pk_fma_f32 v[6:7], v[42:43], s[56:57], v[6:7] op_sel_hi:[1,0,1]
	v_pk_fma_f32 v[8:9], v[40:41], s[56:57], v[8:9] op_sel_hi:[1,0,1]
	v_pk_fma_f32 v[10:11], v[42:43], s[58:59], v[10:11] op_sel_hi:[1,0,1]
	v_pk_fma_f32 v[12:13], v[40:41], s[58:59], v[12:13] op_sel_hi:[1,0,1]
	v_pk_fma_f32 v[14:15], v[42:43], s[64:65], v[14:15] op_sel_hi:[1,0,1]
	v_pk_fma_f32 v[16:17], v[40:41], s[64:65], v[16:17] op_sel_hi:[1,0,1]
	v_pk_fma_f32 v[4:5], v[42:43], s[66:67], v[4:5] op_sel_hi:[1,0,1]
	v_pk_fma_f32 v[2:3], v[40:41], s[66:67], v[2:3] op_sel_hi:[1,0,1]
	v_readlane_b32 s10, v66, s78
	s_waitcnt vmcnt(0)
	v_pk_fma_f32 v[6:7], v[46:47], s[68:69], v[6:7] op_sel_hi:[1,0,1]
	v_pk_fma_f32 v[8:9], v[44:45], s[68:69], v[8:9] op_sel_hi:[1,0,1]
	v_pk_fma_f32 v[10:11], v[46:47], s[70:71], v[10:11] op_sel_hi:[1,0,1]
	v_pk_fma_f32 v[28:29], v[44:45], s[70:71], v[12:13] op_sel_hi:[1,0,1]
	v_pk_fma_f32 v[30:31], v[46:47], s[74:75], v[14:15] op_sel_hi:[1,0,1]
	v_pk_fma_f32 v[32:33], v[44:45], s[74:75], v[16:17] op_sel_hi:[1,0,1]
	v_pk_fma_f32 v[4:5], v[46:47], s[72:73], v[4:5] op_sel_hi:[1,0,1]
	v_pk_fma_f32 v[2:3], v[44:45], s[72:73], v[2:3] op_sel_hi:[1,0,1]
	v_pk_fma_f32 v[16:17], v[20:21], s[76:77], v[6:7] op_sel_hi:[1,0,1]
	v_pk_fma_f32 v[14:15], v[18:19], s[76:77], v[8:9] op_sel_hi:[1,0,1]
	v_pk_fma_f32 v[12:13], v[20:21], s[36:37], v[10:11] op_sel_hi:[1,0,1]
	v_pk_fma_f32 v[10:11], v[18:19], s[36:37], v[28:29] op_sel_hi:[1,0,1]
	v_pk_fma_f32 v[8:9], v[20:21], s[24:25], v[30:31] op_sel_hi:[1,0,1]
	v_pk_fma_f32 v[6:7], v[18:19], s[24:25], v[32:33] op_sel_hi:[1,0,1]
	v_pk_fma_f32 v[4:5], v[20:21], s[10:11], v[4:5] op_sel_hi:[1,0,1]
	v_pk_fma_f32 v[2:3], v[18:19], s[10:11], v[2:3] op_sel_hi:[1,0,1]
	s_cbranch_scc1 .LBB0_19
; __device__ __forceinline__ void p0_prologue(Frame& F) {
;     ...
;                 { const float x0 = F.c[0 * D + kbase + lane], x1 = F.c[1 * D + kbase + lane], x2 = F.c[2 * D + kbase + lane], x3 = F.c[3 * D + kbase + lane];
;                   s0 = x0 / (1.f + expf(-x0)); s1 = x1 / (1.f + expf(-x1)); s2 = x2 / (1.f + expf(-x2)); s3 = x3 / (1.f + expf(-x3)); }
	global_load_dword v28, v[24:25], off offset:512
	s_or_b32 s0, s62, 0x80
	v_add_u32_e32 v18, s0, v58
	v_readlane_b32 s4, v245, 29
	v_add_u32_e32 v20, s0, v59
	v_ashrrev_i32_e32 v19, 31, v18
	v_readlane_b32 s6, v245, 31
	v_readlane_b32 s7, v245, 32
	v_ashrrev_i32_e32 v21, 31, v20
	v_add_u32_e32 v26, s0, v60
	v_lshl_add_u64 v[18:19], v[18:19], 2, s[6:7]
	v_lshl_add_u64 v[20:21], v[20:21], 2, s[6:7]
	v_ashrrev_i32_e32 v27, 31, v26
	v_lshl_add_u64 v[26:27], v[26:27], 2, s[6:7]
	global_load_dword v18, v[18:19], off
	s_nop 0
	global_load_dword v19, v[20:21], off
	s_nop 0
	global_load_dword v20, v[26:27], off
	s_mov_b32 s63, 0
	v_readlane_b32 s5, v245, 30
	v_readlane_b32 s8, v245, 33
	v_readlane_b32 s9, v245, 34
	v_readlane_b32 s10, v245, 35
	v_readlane_b32 s11, v245, 36
	v_readlane_b32 s12, v245, 37
	v_readlane_b32 s13, v245, 38
	v_readlane_b32 s14, v245, 39
	v_readlane_b32 s15, v245, 40
	v_readlane_b32 s16, v245, 41
	v_readlane_b32 s17, v245, 42
	v_readlane_b32 s18, v245, 43
	v_readlane_b32 s19, v245, 44
	s_waitcnt vmcnt(3)
	v_mul_f32_e32 v21, 0xbfb8aa3b, v28
	v_rndne_f32_e32 v26, v21
	v_fma_f32 v27, v28, s41, -v21
	v_sub_f32_e32 v21, v21, v26
	v_fmac_f32_e32 v27, 0xb2a5705f, v28
	v_add_f32_e32 v21, v21, v27
	v_cvt_i32_f32_e32 v26, v26
	v_exp_f32_e32 v21, v21
	v_cmp_nlt_f32_e32 vcc, s43, v28
	v_ldexp_f32 v21, v21, v26
	s_waitcnt vmcnt(2)
	v_mul_f32_e32 v27, 0xbfb8aa3b, v18
	s_waitcnt vmcnt(1)
	v_mul_f32_e32 v29, 0xbfb8aa3b, v19
	v_fma_f32 v31, v18, s41, -v27
	v_rndne_f32_e32 v32, v27
	s_waitcnt vmcnt(0)
	v_mul_f32_e32 v30, 0xbfb8aa3b, v20
	v_fma_f32 v33, v19, s41, -v29
	v_rndne_f32_e32 v34, v29
	v_fmac_f32_e32 v31, 0xb2a5705f, v18
	v_sub_f32_e32 v27, v27, v32
	v_fma_f32 v35, v20, s41, -v30
	v_rndne_f32_e32 v36, v30
	v_fmac_f32_e32 v33, 0xb2a5705f, v19
	v_sub_f32_e32 v29, v29, v34
	v_add_f32_e32 v27, v27, v31
	v_cvt_i32_f32_e32 v32, v32
	v_fmac_f32_e32 v35, 0xb2a5705f, v20
	v_sub_f32_e32 v30, v30, v36
	v_add_f32_e32 v29, v29, v33
	v_exp_f32_e32 v26, v27
	v_cndmask_b32_e32 v21, 0, v21, vcc
	v_cmp_ngt_f32_e32 vcc, s45, v28
	v_cvt_i32_f32_e32 v34, v34
	v_add_f32_e32 v30, v30, v35
	v_exp_f32_e32 v27, v29
	v_cndmask_b32_e32 v21, v61, v21, vcc
	v_cvt_i32_f32_e32 v36, v36
	v_exp_f32_e32 v29, v30
	v_add_f32_e32 v21, 1.0, v21
	v_div_scale_f32 v30, s[0:1], v21, v21, v28
	v_ldexp_f32 v26, v26, v32
	v_cmp_nlt_f32_e64 s[0:1], s43, v18
	v_ldexp_f32 v27, v27, v34
	v_ldexp_f32 v29, v29, v36
	v_cndmask_b32_e64 v26, 0, v26, s[0:1]
	v_cmp_nlt_f32_e64 s[0:1], s43, v19
	v_rcp_f32_e32 v32, v30
	v_div_scale_f32 v31, vcc, v28, v21, v28
	v_cndmask_b32_e64 v27, 0, v27, s[0:1]
	v_cmp_nlt_f32_e64 s[0:1], s43, v20
	v_fma_f32 v37, -v30, v32, 1.0
	v_fmac_f32_e32 v32, v37, v32
	v_cndmask_b32_e64 v29, 0, v29, s[0:1]
	v_cmp_ngt_f32_e64 s[0:1], s45, v18
	v_mul_f32_e32 v37, v31, v32
	v_fma_f32 v40, -v30, v37, v31
	v_cndmask_b32_e64 v26, v61, v26, s[0:1]
	v_cmp_ngt_f32_e64 s[0:1], s45, v19
	v_add_f32_e32 v26, 1.0, v26
	v_fmac_f32_e32 v37, v40, v32
	v_cndmask_b32_e64 v27, v61, v27, s[0:1]
	v_cmp_ngt_f32_e64 s[0:1], s45, v20
	v_add_f32_e32 v27, 1.0, v27
	v_div_scale_f32 v35, s[2:3], v27, v27, v19
	v_cndmask_b32_e64 v29, v61, v29, s[0:1]
	v_div_scale_f32 v33, s[0:1], v26, v26, v18
	v_rcp_f32_e32 v38, v33
	v_div_scale_f32 v34, s[0:1], v18, v26, v18
	v_rcp_f32_e32 v39, v35
	v_fma_f32 v40, -v33, v38, 1.0
	v_fma_f32 v30, -v30, v37, v31
	v_fmac_f32_e32 v38, v40, v38
	v_div_fmas_f32 v30, v30, v32, v37
	v_mul_f32_e32 v31, v34, v38
	v_div_fixup_f32 v63, v30, v21, v28
	v_fma_f32 v21, -v33, v31, v34
	v_fmac_f32_e32 v31, v21, v38
	v_fma_f32 v41, -v35, v39, 1.0
	v_fma_f32 v21, -v33, v31, v34
	s_mov_b64 vcc, s[0:1]
	v_add_f32_e32 v29, 1.0, v29
	v_div_scale_f32 v36, s[2:3], v19, v27, v19
	v_fmac_f32_e32 v39, v41, v39
	v_div_fmas_f32 v21, v21, v38, v31
	v_mul_f32_e32 v32, v36, v39
	v_div_fixup_f32 v64, v21, v26, v18
	v_div_scale_f32 v18, s[0:1], v29, v29, v20
	v_fma_f32 v28, -v35, v32, v36
	v_rcp_f32_e32 v21, v18
	v_fmac_f32_e32 v32, v28, v39
	v_fma_f32 v28, -v35, v32, v36
	s_mov_b64 vcc, s[2:3]
	v_div_fmas_f32 v26, v28, v39, v32
	v_div_fixup_f32 v65, v26, v27, v19
	v_fma_f32 v19, -v18, v21, 1.0
	v_fmac_f32_e32 v21, v19, v21
	v_div_scale_f32 v19, vcc, v20, v29, v20
	v_mul_f32_e32 v26, v19, v21
	v_fma_f32 v27, -v18, v26, v19
	v_fmac_f32_e32 v26, v27, v21
	v_fma_f32 v18, -v18, v26, v19
	v_readlane_b32 s0, v244, 1
	v_div_fmas_f32 v18, v18, v21, v26
	v_readlane_b32 s1, v244, 2
	v_div_fixup_f32 v66, v18, v29, v20
	s_nop 0
	v_lshl_add_u64 v[26:27], s[0:1], 0, v[22:23]
; __device__ __forceinline__ float rdlane(float v, int l) { return __int_as_float(__builtin_amdgcn_readlane(__float_as_int(v), l)); }
; __device__ __forceinline__ void p0_prologue(Frame& F) {
;     ...
;                 for (int kk = 0; kk < 64; ++kk) { const f32x4 w = *(const f32x4*)(wp + (size_t)kk * NADA);
;                     a0 += w * rdlane(s0, kk); a1 += w * rdlane(s1, kk); a2 += w * rdlane(s2, kk); a3 += w * rdlane(s3, kk); }
.LBB0_21:
	v_add_co_u32_e32 v54, vcc, 0xffe98000, v26
	v_add_co_u32_e64 v56, s[2:3], s67, v26
	s_nop 0
	v_addc_co_u32_e32 v55, vcc, -1, v27, vcc
	global_load_dwordx4 v[68:71], v[54:55], off nt
	v_readlane_b32 s68, v63, s63
	v_readlane_b32 s66, v64, s63
	v_readlane_b32 s64, v65, s63
	v_readlane_b32 s34, v66, s63
	v_addc_co_u32_e64 v57, s[0:1], -1, v27, s[2:3]
	s_add_i32 s36, s63, 1
	v_add_co_u32_e64 v52, s[4:5], s69, v26
	v_add_co_u32_e64 v30, s[16:17], s49, v26
	v_add_co_u32_e64 v32, s[18:19], s51, v26
	v_add_co_u32_e64 v36, s[20:21], s53, v26
	v_add_co_u32_e64 v40, s[22:23], s55, v26
	v_addc_co_u32_e64 v53, s[0:1], -1, v27, s[4:5]
	v_addc_co_u32_e64 v31, s[0:1], -1, v27, s[16:17]
	v_addc_co_u32_e64 v33, s[0:1], -1, v27, s[18:19]
	v_addc_co_u32_e64 v37, s[0:1], -1, v27, s[20:21]
	v_addc_co_u32_e64 v41, s[0:1], -1, v27, s[22:23]
	v_readlane_b32 s16, v63, s36
	v_readlane_b32 s18, v64, s36
	v_readlane_b32 s20, v65, s36
	v_readlane_b32 s22, v66, s36
	s_add_i32 s38, s63, 2
	v_add_co_u32_e64 v48, s[6:7], s71, v26
	v_add_co_u32_e64 v46, s[26:27], s59, v26
	v_add_co_u32_e64 v50, s[28:29], s65, v26
	v_addc_co_u32_e64 v49, s[0:1], -1, v27, s[6:7]
	v_addc_co_u32_e64 v47, s[0:1], -1, v27, s[26:27]
	v_addc_co_u32_e64 v51, s[0:1], -1, v27, s[28:29]
	v_readlane_b32 s26, v63, s38
	v_readlane_b32 s28, v64, s38
	v_readlane_b32 s54, v65, s38
	v_readlane_b32 s48, v66, s38
	s_add_i32 s42, s63, 3
	v_add_co_u32_e64 v44, s[8:9], s73, v26
	v_readlane_b32 s36, v63, s42
	s_nop 0
	v_addc_co_u32_e64 v45, s[0:1], -1, v27, s[8:9]
	v_readlane_b32 s38, v64, s42
	v_readlane_b32 s40, v65, s42
	v_readlane_b32 s42, v66, s42
	s_add_i32 s52, s63, 4
	v_add_co_u32_e64 v38, s[10:11], s75, v26
	v_readlane_b32 s44, v63, s52
	s_nop 0
	v_addc_co_u32_e64 v39, s[0:1], -1, v27, s[10:11]
	v_readlane_b32 s46, v64, s52
	v_readlane_b32 s50, v65, s52
	v_readlane_b32 s58, v66, s52
	s_add_i32 s56, s63, 5
	v_add_co_u32_e64 v34, s[12:13], s77, v26
	s_add_i32 s87, s63, 11
	s_nop 0
	v_addc_co_u32_e64 v35, s[0:1], -1, v27, s[12:13]
	v_readlane_b32 s86, v63, s56
	v_readlane_b32 s78, v64, s56
	v_readlane_b32 s74, v65, s56
	v_readlane_b32 s70, v66, s56
	global_load_dwordx4 v[18:21], v[26:27], off nt
	s_add_i32 s85, s63, 6
	v_add_co_u32_e64 v28, s[14:15], s47, v26
	s_waitcnt vmcnt(1)
	v_pk_fma_f32 v[14:15], v[68:69], s[68:69], v[14:15] op_sel_hi:[1,0,1]
	v_pk_fma_f32 v[10:11], v[68:69], s[66:67], v[10:11] op_sel_hi:[1,0,1]
	v_pk_fma_f32 v[6:7], v[68:69], s[64:65], v[6:7] op_sel_hi:[1,0,1]
	v_pk_fma_f32 v[54:55], v[70:71], s[34:35], v[4:5] op_sel_hi:[1,0,1]
	v_pk_fma_f32 v[68:69], v[68:69], s[34:35], v[2:3] op_sel_hi:[1,0,1]
	global_load_dwordx4 v[2:5], v[56:57], off nt
	v_pk_fma_f32 v[16:17], v[70:71], s[68:69], v[16:17] op_sel_hi:[1,0,1]
	v_pk_fma_f32 v[12:13], v[70:71], s[66:67], v[12:13] op_sel_hi:[1,0,1]
	v_pk_fma_f32 v[8:9], v[70:71], s[64:65], v[8:9] op_sel_hi:[1,0,1]
	v_add_co_u32_e64 v42, s[24:25], s57, v26
	v_addc_co_u32_e64 v29, s[0:1], -1, v27, s[14:15]
	s_nop 0
	v_addc_co_u32_e64 v43, s[0:1], -1, v27, s[24:25]
	v_readlane_b32 s72, v63, s85
	v_readlane_b32 s76, v64, s85
	s_add_i32 s88, s63, 7
	v_readlane_b32 s52, v65, s85
	v_readlane_b32 s24, v66, s85
	s_add_i32 s89, s63, 8
	v_readlane_b32 s10, v63, s88
	v_readlane_b32 s0, v64, s88
	v_readlane_b32 s2, v65, s88
	v_readlane_b32 s4, v66, s88
	s_add_i32 s91, s63, 9
	v_readlane_b32 s6, v63, s89
	v_readlane_b32 s8, v64, s89
	v_readlane_b32 s14, v65, s89
	v_readlane_b32 s12, v66, s89
	s_add_i32 s90, s63, 10
	v_readlane_b32 s34, v66, s90
	s_add_i32 s84, s63, 12
	v_readlane_b32 s56, v63, s87
	s_add_i32 s83, s63, 13
	s_add_i32 s82, s63, 14
	v_readlane_b32 s64, v65, s83
	v_readlane_b32 s66, v66, s83
	s_add_i32 s81, s63, 15
	v_readlane_b32 s68, v63, s82
	s_add_i32 s63, s63, 16
	s_cmp_lg_u32 s63, 64
	s_waitcnt vmcnt(0)
	v_pk_fma_f32 v[16:17], v[4:5], s[16:17], v[16:17] op_sel_hi:[1,0,1]
	v_pk_fma_f32 v[14:15], v[2:3], s[16:17], v[14:15] op_sel_hi:[1,0,1]
	v_pk_fma_f32 v[12:13], v[4:5], s[18:19], v[12:13] op_sel_hi:[1,0,1]
	v_pk_fma_f32 v[10:11], v[2:3], s[18:19], v[10:11] op_sel_hi:[1,0,1]
	v_pk_fma_f32 v[8:9], v[4:5], s[20:21], v[8:9] op_sel_hi:[1,0,1]
	v_pk_fma_f32 v[6:7], v[2:3], s[20:21], v[6:7] op_sel_hi:[1,0,1]
	v_pk_fma_f32 v[54:55], v[4:5], s[22:23], v[54:55] op_sel_hi:[1,0,1]
	v_pk_fma_f32 v[56:57], v[2:3], s[22:23], v[68:69] op_sel_hi:[1,0,1]
	global_load_dwordx4 v[2:5], v[52:53], off nt
	v_readlane_b32 s16, v63, s91
	v_readlane_b32 s18, v64, s91
	v_readlane_b32 s20, v65, s91
	v_readlane_b32 s22, v66, s91
	s_waitcnt vmcnt(0)
	v_pk_fma_f32 v[16:17], v[4:5], s[26:27], v[16:17] op_sel_hi:[1,0,1]
	v_pk_fma_f32 v[14:15], v[2:3], s[26:27], v[14:15] op_sel_hi:[1,0,1]
	v_pk_fma_f32 v[12:13], v[4:5], s[28:29], v[12:13] op_sel_hi:[1,0,1]
	v_pk_fma_f32 v[10:11], v[2:3], s[28:29], v[10:11] op_sel_hi:[1,0,1]
	v_pk_fma_f32 v[8:9], v[4:5], s[54:55], v[8:9] op_sel_hi:[1,0,1]
	v_pk_fma_f32 v[6:7], v[2:3], s[54:55], v[6:7] op_sel_hi:[1,0,1]
	v_pk_fma_f32 v[52:53], v[4:5], s[48:49], v[54:55] op_sel_hi:[1,0,1]
	v_pk_fma_f32 v[54:55], v[2:3], s[48:49], v[56:57] op_sel_hi:[1,0,1]
	global_load_dwordx4 v[2:5], v[48:49], off nt
	v_readlane_b32 s26, v63, s90
	v_readlane_b32 s28, v64, s90
	v_readlane_b32 s54, v65, s90
	v_readlane_b32 s48, v65, s84
	s_waitcnt vmcnt(0)
	v_pk_fma_f32 v[16:17], v[4:5], s[36:37], v[16:17] op_sel_hi:[1,0,1]
	v_pk_fma_f32 v[14:15], v[2:3], s[36:37], v[14:15] op_sel_hi:[1,0,1]
	v_pk_fma_f32 v[12:13], v[4:5], s[38:39], v[12:13] op_sel_hi:[1,0,1]
	v_pk_fma_f32 v[10:11], v[2:3], s[38:39], v[10:11] op_sel_hi:[1,0,1]
	v_pk_fma_f32 v[8:9], v[4:5], s[40:41], v[8:9] op_sel_hi:[1,0,1]
	v_pk_fma_f32 v[6:7], v[2:3], s[40:41], v[6:7] op_sel_hi:[1,0,1]
	v_pk_fma_f32 v[48:49], v[4:5], s[42:43], v[52:53] op_sel_hi:[1,0,1]
	v_pk_fma_f32 v[52:53], v[2:3], s[42:43], v[54:55] op_sel_hi:[1,0,1]
	global_load_dwordx4 v[2:5], v[44:45], off nt
	v_readlane_b32 s36, v64, s87
	v_readlane_b32 s38, v65, s87
	v_readlane_b32 s40, v66, s87
	v_readlane_b32 s42, v63, s84
	s_waitcnt vmcnt(0)
; __device__ __forceinline__ float rdlane(float v, int l) { return __int_as_float(__builtin_amdgcn_readlane(__float_as_int(v), l)); }
; __device__ __forceinline__ void p0_prologue(Frame& F) {
;     ...
;                 for (int kk = 0; kk < 64; ++kk) { const f32x4 w = *(const f32x4*)(wp + (size_t)kk * NADA);
;                     a0 += w * rdlane(s0, kk); a1 += w * rdlane(s1, kk); a2 += w * rdlane(s2, kk); a3 += w * rdlane(s3, kk); }
	v_pk_fma_f32 v[16:17], v[4:5], s[44:45], v[16:17] op_sel_hi:[1,0,1]
	v_pk_fma_f32 v[14:15], v[2:3], s[44:45], v[14:15] op_sel_hi:[1,0,1]
	v_pk_fma_f32 v[12:13], v[4:5], s[46:47], v[12:13] op_sel_hi:[1,0,1]
	v_pk_fma_f32 v[10:11], v[2:3], s[46:47], v[10:11] op_sel_hi:[1,0,1]
	v_pk_fma_f32 v[8:9], v[4:5], s[50:51], v[8:9] op_sel_hi:[1,0,1]
	v_pk_fma_f32 v[6:7], v[2:3], s[50:51], v[6:7] op_sel_hi:[1,0,1]
	v_pk_fma_f32 v[44:45], v[4:5], s[58:59], v[48:49] op_sel_hi:[1,0,1]
	v_pk_fma_f32 v[48:49], v[2:3], s[58:59], v[52:53] op_sel_hi:[1,0,1]
	global_load_dwordx4 v[2:5], v[38:39], off nt
	v_readlane_b32 s44, v64, s84
	v_readlane_b32 s46, v66, s84
	v_readlane_b32 s50, v63, s83
	v_readlane_b32 s58, v64, s83
	s_waitcnt vmcnt(0)
	v_pk_fma_f32 v[16:17], v[4:5], s[86:87], v[16:17] op_sel_hi:[1,0,1]
	v_pk_fma_f32 v[14:15], v[2:3], s[86:87], v[14:15] op_sel_hi:[1,0,1]
	v_pk_fma_f32 v[12:13], v[4:5], s[78:79], v[12:13] op_sel_hi:[1,0,1]
	v_pk_fma_f32 v[10:11], v[2:3], s[78:79], v[10:11] op_sel_hi:[1,0,1]
	v_pk_fma_f32 v[52:53], v[4:5], s[74:75], v[8:9] op_sel_hi:[1,0,1]
	v_pk_fma_f32 v[54:55], v[2:3], s[74:75], v[6:7] op_sel_hi:[1,0,1]
	v_pk_fma_f32 v[56:57], v[4:5], s[70:71], v[44:45] op_sel_hi:[1,0,1]
	v_pk_fma_f32 v[48:49], v[2:3], s[70:71], v[48:49] op_sel_hi:[1,0,1]
	global_load_dwordx4 v[2:5], v[34:35], off nt
	v_readlane_b32 s70, v64, s82
	v_readlane_b32 s74, v65, s82
	v_lshl_add_u64 v[26:27], v[26:27], 0, s[60:61]
	s_waitcnt vmcnt(0)
	v_pk_fma_f32 v[68:69], v[4:5], s[72:73], v[16:17] op_sel_hi:[1,0,1]
	v_pk_fma_f32 v[70:71], v[2:3], s[72:73], v[14:15] op_sel_hi:[1,0,1]
	v_pk_fma_f32 v[72:73], v[4:5], s[76:77], v[12:13] op_sel_hi:[1,0,1]
	v_pk_fma_f32 v[74:75], v[2:3], s[76:77], v[10:11] op_sel_hi:[1,0,1]
	global_load_dwordx4 v[6:9], v[28:29], off nt
	global_load_dwordx4 v[10:13], v[30:31], off nt
	global_load_dwordx4 v[14:17], v[32:33], off nt
	s_nop 0
	global_load_dwordx4 v[28:31], v[36:37], off nt
	global_load_dwordx4 v[32:35], v[40:41], off nt
	s_nop 0
	global_load_dwordx4 v[36:39], v[42:43], off nt
	s_nop 0
	global_load_dwordx4 v[40:43], v[46:47], off nt
	s_nop 0
	global_load_dwordx4 v[44:47], v[50:51], off nt
	v_pk_fma_f32 v[50:51], v[4:5], s[52:53], v[52:53] op_sel_hi:[1,0,1]
	v_pk_fma_f32 v[52:53], v[2:3], s[52:53], v[54:55] op_sel_hi:[1,0,1]
	v_pk_fma_f32 v[4:5], v[4:5], s[24:25], v[56:57] op_sel_hi:[1,0,1]
	v_pk_fma_f32 v[2:3], v[2:3], s[24:25], v[48:49] op_sel_hi:[1,0,1]
	v_readlane_b32 s72, v66, s82
	v_readlane_b32 s76, v63, s81
	v_readlane_b32 s52, v64, s81
	v_readlane_b32 s24, v65, s81
	s_waitcnt vmcnt(7)
	v_pk_fma_f32 v[48:49], v[8:9], s[10:11], v[68:69] op_sel_hi:[1,0,1]
	v_pk_fma_f32 v[54:55], v[6:7], s[10:11], v[70:71] op_sel_hi:[1,0,1]
	v_pk_fma_f32 v[56:57], v[8:9], s[0:1], v[72:73] op_sel_hi:[1,0,1]
	v_pk_fma_f32 v[68:69], v[6:7], s[0:1], v[74:75] op_sel_hi:[1,0,1]
	v_pk_fma_f32 v[50:51], v[8:9], s[2:3], v[50:51] op_sel_hi:[1,0,1]
	v_pk_fma_f32 v[52:53], v[6:7], s[2:3], v[52:53] op_sel_hi:[1,0,1]
	v_pk_fma_f32 v[4:5], v[8:9], s[4:5], v[4:5] op_sel_hi:[1,0,1]
	v_pk_fma_f32 v[2:3], v[6:7], s[4:5], v[2:3] op_sel_hi:[1,0,1]
	s_waitcnt vmcnt(6)
	v_pk_fma_f32 v[6:7], v[12:13], s[6:7], v[48:49] op_sel_hi:[1,0,1]
	v_pk_fma_f32 v[8:9], v[10:11], s[6:7], v[54:55] op_sel_hi:[1,0,1]
	v_pk_fma_f32 v[48:49], v[12:13], s[8:9], v[56:57] op_sel_hi:[1,0,1]
	v_pk_fma_f32 v[54:55], v[10:11], s[8:9], v[68:69] op_sel_hi:[1,0,1]
	v_pk_fma_f32 v[50:51], v[12:13], s[14:15], v[50:51] op_sel_hi:[1,0,1]
	v_pk_fma_f32 v[52:53], v[10:11], s[14:15], v[52:53] op_sel_hi:[1,0,1]
	v_pk_fma_f32 v[4:5], v[12:13], s[12:13], v[4:5] op_sel_hi:[1,0,1]
	v_pk_fma_f32 v[2:3], v[10:11], s[12:13], v[2:3] op_sel_hi:[1,0,1]
	s_waitcnt vmcnt(5)
	v_pk_fma_f32 v[6:7], v[16:17], s[16:17], v[6:7] op_sel_hi:[1,0,1]
	v_pk_fma_f32 v[8:9], v[14:15], s[16:17], v[8:9] op_sel_hi:[1,0,1]
	v_pk_fma_f32 v[10:11], v[16:17], s[18:19], v[48:49] op_sel_hi:[1,0,1]
	v_pk_fma_f32 v[12:13], v[14:15], s[18:19], v[54:55] op_sel_hi:[1,0,1]
	v_pk_fma_f32 v[48:49], v[16:17], s[20:21], v[50:51] op_sel_hi:[1,0,1]
	v_pk_fma_f32 v[50:51], v[14:15], s[20:21], v[52:53] op_sel_hi:[1,0,1]
	v_pk_fma_f32 v[4:5], v[16:17], s[22:23], v[4:5] op_sel_hi:[1,0,1]
	v_pk_fma_f32 v[2:3], v[14:15], s[22:23], v[2:3] op_sel_hi:[1,0,1]
	s_waitcnt vmcnt(4)
	v_pk_fma_f32 v[6:7], v[30:31], s[26:27], v[6:7] op_sel_hi:[1,0,1]
	v_pk_fma_f32 v[8:9], v[28:29], s[26:27], v[8:9] op_sel_hi:[1,0,1]
	v_pk_fma_f32 v[10:11], v[30:31], s[28:29], v[10:11] op_sel_hi:[1,0,1]
	v_pk_fma_f32 v[12:13], v[28:29], s[28:29], v[12:13] op_sel_hi:[1,0,1]
	v_pk_fma_f32 v[14:15], v[30:31], s[54:55], v[48:49] op_sel_hi:[1,0,1]
	v_pk_fma_f32 v[16:17], v[28:29], s[54:55], v[50:51] op_sel_hi:[1,0,1]
	v_pk_fma_f32 v[4:5], v[30:31], s[34:35], v[4:5] op_sel_hi:[1,0,1]
	v_pk_fma_f32 v[2:3], v[28:29], s[34:35], v[2:3] op_sel_hi:[1,0,1]
	s_waitcnt vmcnt(3)
	v_pk_fma_f32 v[6:7], v[34:35], s[56:57], v[6:7] op_sel_hi:[1,0,1]
	v_pk_fma_f32 v[8:9], v[32:33], s[56:57], v[8:9] op_sel_hi:[1,0,1]
	v_pk_fma_f32 v[10:11], v[34:35], s[36:37], v[10:11] op_sel_hi:[1,0,1]
	v_pk_fma_f32 v[12:13], v[32:33], s[36:37], v[12:13] op_sel_hi:[1,0,1]
	v_pk_fma_f32 v[14:15], v[34:35], s[38:39], v[14:15] op_sel_hi:[1,0,1]
	v_pk_fma_f32 v[16:17], v[32:33], s[38:39], v[16:17] op_sel_hi:[1,0,1]
	v_pk_fma_f32 v[4:5], v[34:35], s[40:41], v[4:5] op_sel_hi:[1,0,1]
	v_pk_fma_f32 v[2:3], v[32:33], s[40:41], v[2:3] op_sel_hi:[1,0,1]
	s_waitcnt vmcnt(2)
; __device__ __forceinline__ float rdlane(float v, int l) { return __int_as_float(__builtin_amdgcn_readlane(__float_as_int(v), l)); }
; __device__ __forceinline__ void p0_prologue(Frame& F) {
;     ...
;                 { const float x0 = F.c[0 * D + kbase + lane], x1 = F.c[1 * D + kbase + lane], x2 = F.c[2 * D + kbase + lane], x3 = F.c[3 * D + kbase + lane];
;                   s0 = x0 / (1.f + expf(-x0)); s1 = x1 / (1.f + expf(-x1)); s2 = x2 / (1.f + expf(-x2)); s3 = x3 / (1.f + expf(-x3)); }
;     ...
;                 for (int kk = 0; kk < 64; ++kk) { const f32x4 w = *(const f32x4*)(wp + (size_t)kk * NADA);
;                     a0 += w * rdlane(s0, kk); a1 += w * rdlane(s1, kk); a2 += w * rdlane(s2, kk); a3 += w * rdlane(s3, kk); }
	v_pk_fma_f32 v[6:7], v[38:39], s[42:43], v[6:7] op_sel_hi:[1,0,1]
	v_pk_fma_f32 v[8:9], v[36:37], s[42:43], v[8:9] op_sel_hi:[1,0,1]
	v_pk_fma_f32 v[10:11], v[38:39], s[44:45], v[10:11] op_sel_hi:[1,0,1]
	v_pk_fma_f32 v[12:13], v[36:37], s[44:45], v[12:13] op_sel_hi:[1,0,1]
	v_pk_fma_f32 v[14:15], v[38:39], s[48:49], v[14:15] op_sel_hi:[1,0,1]
	v_pk_fma_f32 v[16:17], v[36:37], s[48:49], v[16:17] op_sel_hi:[1,0,1]
	v_pk_fma_f32 v[4:5], v[38:39], s[46:47], v[4:5] op_sel_hi:[1,0,1]
	v_pk_fma_f32 v[2:3], v[36:37], s[46:47], v[2:3] op_sel_hi:[1,0,1]
	s_waitcnt vmcnt(1)
	v_pk_fma_f32 v[6:7], v[42:43], s[50:51], v[6:7] op_sel_hi:[1,0,1]
	v_pk_fma_f32 v[8:9], v[40:41], s[50:51], v[8:9] op_sel_hi:[1,0,1]
	v_pk_fma_f32 v[10:11], v[42:43], s[58:59], v[10:11] op_sel_hi:[1,0,1]
	v_pk_fma_f32 v[12:13], v[40:41], s[58:59], v[12:13] op_sel_hi:[1,0,1]
	v_pk_fma_f32 v[14:15], v[42:43], s[64:65], v[14:15] op_sel_hi:[1,0,1]
	v_pk_fma_f32 v[16:17], v[40:41], s[64:65], v[16:17] op_sel_hi:[1,0,1]
	v_pk_fma_f32 v[4:5], v[42:43], s[66:67], v[4:5] op_sel_hi:[1,0,1]
	v_pk_fma_f32 v[2:3], v[40:41], s[66:67], v[2:3] op_sel_hi:[1,0,1]
	v_readlane_b32 s10, v66, s81
	s_waitcnt vmcnt(0)
	v_pk_fma_f32 v[6:7], v[46:47], s[68:69], v[6:7] op_sel_hi:[1,0,1]
	v_pk_fma_f32 v[8:9], v[44:45], s[68:69], v[8:9] op_sel_hi:[1,0,1]
	v_pk_fma_f32 v[10:11], v[46:47], s[70:71], v[10:11] op_sel_hi:[1,0,1]
	v_pk_fma_f32 v[28:29], v[44:45], s[70:71], v[12:13] op_sel_hi:[1,0,1]
	v_pk_fma_f32 v[30:31], v[46:47], s[74:75], v[14:15] op_sel_hi:[1,0,1]
	v_pk_fma_f32 v[32:33], v[44:45], s[74:75], v[16:17] op_sel_hi:[1,0,1]
	v_pk_fma_f32 v[4:5], v[46:47], s[72:73], v[4:5] op_sel_hi:[1,0,1]
	v_pk_fma_f32 v[2:3], v[44:45], s[72:73], v[2:3] op_sel_hi:[1,0,1]
	v_pk_fma_f32 v[16:17], v[20:21], s[76:77], v[6:7] op_sel_hi:[1,0,1]
	v_pk_fma_f32 v[14:15], v[18:19], s[76:77], v[8:9] op_sel_hi:[1,0,1]
	v_pk_fma_f32 v[12:13], v[20:21], s[52:53], v[10:11] op_sel_hi:[1,0,1]
	v_pk_fma_f32 v[10:11], v[18:19], s[52:53], v[28:29] op_sel_hi:[1,0,1]
	v_pk_fma_f32 v[8:9], v[20:21], s[24:25], v[30:31] op_sel_hi:[1,0,1]
	v_pk_fma_f32 v[6:7], v[18:19], s[24:25], v[32:33] op_sel_hi:[1,0,1]
	v_pk_fma_f32 v[4:5], v[20:21], s[10:11], v[4:5] op_sel_hi:[1,0,1]
	v_pk_fma_f32 v[2:3], v[18:19], s[10:11], v[2:3] op_sel_hi:[1,0,1]
	s_cbranch_scc1 .LBB0_21
	global_load_dword v26, v[24:25], off offset:768
	s_or_b32 s0, s62, 0xc0
	v_add_u32_e32 v18, s0, v58
	v_readlane_b32 s4, v245, 29
	v_add_u32_e32 v20, s0, v59
	v_ashrrev_i32_e32 v19, 31, v18
	v_readlane_b32 s6, v245, 31
	v_readlane_b32 s7, v245, 32
	v_ashrrev_i32_e32 v21, 31, v20
	v_add_u32_e32 v24, s0, v60
	v_lshl_add_u64 v[18:19], v[18:19], 2, s[6:7]
	v_lshl_add_u64 v[20:21], v[20:21], 2, s[6:7]
	v_ashrrev_i32_e32 v25, 31, v24
	v_lshl_add_u64 v[24:25], v[24:25], 2, s[6:7]
	global_load_dword v18, v[18:19], off
	s_nop 0
	global_load_dword v19, v[20:21], off
	s_nop 0
	global_load_dword v20, v[24:25], off
	v_lshl_add_u64 v[22:23], s[94:95], 0, v[22:23]
	s_mov_b32 s63, 0
	v_readlane_b32 s96, v245, 26
	v_readlane_b32 s5, v245, 30
	v_readlane_b32 s8, v245, 33
	v_readlane_b32 s9, v245, 34
	v_readlane_b32 s10, v245, 35
	v_readlane_b32 s11, v245, 36
	v_readlane_b32 s12, v245, 37
	v_readlane_b32 s13, v245, 38
	v_readlane_b32 s14, v245, 39
	v_readlane_b32 s15, v245, 40
	v_readlane_b32 s16, v245, 41
	v_readlane_b32 s17, v245, 42
	v_readlane_b32 s18, v245, 43
	v_readlane_b32 s19, v245, 44
	s_waitcnt vmcnt(3)
	v_mul_f32_e32 v21, 0xbfb8aa3b, v26
	v_rndne_f32_e32 v24, v21
	v_fma_f32 v25, v26, s41, -v21
	v_sub_f32_e32 v21, v21, v24
	v_fmac_f32_e32 v25, 0xb2a5705f, v26
	v_add_f32_e32 v21, v21, v25
	v_cvt_i32_f32_e32 v24, v24
	v_exp_f32_e32 v21, v21
	v_cmp_nlt_f32_e32 vcc, s43, v26
	v_ldexp_f32 v21, v21, v24
	s_waitcnt vmcnt(2)
	v_mul_f32_e32 v25, 0xbfb8aa3b, v18
	s_waitcnt vmcnt(1)
	v_mul_f32_e32 v27, 0xbfb8aa3b, v19
	v_fma_f32 v29, v18, s41, -v25
	v_rndne_f32_e32 v30, v25
	s_waitcnt vmcnt(0)
	v_mul_f32_e32 v28, 0xbfb8aa3b, v20
	v_fma_f32 v31, v19, s41, -v27
	v_rndne_f32_e32 v32, v27
	v_fmac_f32_e32 v29, 0xb2a5705f, v18
	v_sub_f32_e32 v25, v25, v30
	v_fma_f32 v33, v20, s41, -v28
	v_rndne_f32_e32 v34, v28
	v_fmac_f32_e32 v31, 0xb2a5705f, v19
	v_sub_f32_e32 v27, v27, v32
	v_add_f32_e32 v25, v25, v29
	v_cvt_i32_f32_e32 v30, v30
	v_fmac_f32_e32 v33, 0xb2a5705f, v20
	v_sub_f32_e32 v28, v28, v34
	v_add_f32_e32 v27, v27, v31
	v_exp_f32_e32 v24, v25
	v_cndmask_b32_e32 v21, 0, v21, vcc
	v_cmp_ngt_f32_e32 vcc, s45, v26
	v_cvt_i32_f32_e32 v32, v32
	v_add_f32_e32 v28, v28, v33
	v_exp_f32_e32 v25, v27
	v_cndmask_b32_e32 v21, v61, v21, vcc
	v_cvt_i32_f32_e32 v34, v34
	v_exp_f32_e32 v27, v28
	v_add_f32_e32 v21, 1.0, v21
	v_div_scale_f32 v28, s[0:1], v21, v21, v26
	v_ldexp_f32 v24, v24, v30
	v_cmp_nlt_f32_e64 s[0:1], s43, v18
	v_ldexp_f32 v25, v25, v32
	v_ldexp_f32 v27, v27, v34
	v_cndmask_b32_e64 v24, 0, v24, s[0:1]
	v_cmp_nlt_f32_e64 s[0:1], s43, v19
	v_rcp_f32_e32 v30, v28
	v_div_scale_f32 v29, vcc, v26, v21, v26
	v_cndmask_b32_e64 v25, 0, v25, s[0:1]
	v_cmp_nlt_f32_e64 s[0:1], s43, v20
	v_fma_f32 v35, -v28, v30, 1.0
	v_fmac_f32_e32 v30, v35, v30
	v_cndmask_b32_e64 v27, 0, v27, s[0:1]
	v_cmp_ngt_f32_e64 s[0:1], s45, v18
	v_mul_f32_e32 v35, v29, v30
	v_fma_f32 v38, -v28, v35, v29
	v_cndmask_b32_e64 v24, v61, v24, s[0:1]
	v_cmp_ngt_f32_e64 s[0:1], s45, v19
	v_add_f32_e32 v24, 1.0, v24
	v_fmac_f32_e32 v35, v38, v30
	v_cndmask_b32_e64 v25, v61, v25, s[0:1]
	v_cmp_ngt_f32_e64 s[0:1], s45, v20
	v_add_f32_e32 v25, 1.0, v25
	v_div_scale_f32 v33, s[2:3], v25, v25, v19
	v_cndmask_b32_e64 v27, v61, v27, s[0:1]
	v_div_scale_f32 v31, s[0:1], v24, v24, v18
	v_rcp_f32_e32 v36, v31
	v_div_scale_f32 v32, s[0:1], v18, v24, v18
	v_rcp_f32_e32 v37, v33
	v_fma_f32 v38, -v31, v36, 1.0
	v_fma_f32 v28, -v28, v35, v29
	v_fmac_f32_e32 v36, v38, v36
	v_div_fmas_f32 v28, v28, v30, v35
	v_mul_f32_e32 v29, v32, v36
	v_div_fixup_f32 v54, v28, v21, v26
	v_fma_f32 v21, -v31, v29, v32
	v_fmac_f32_e32 v29, v21, v36
	v_fma_f32 v39, -v33, v37, 1.0
	v_fma_f32 v21, -v31, v29, v32
	s_mov_b64 vcc, s[0:1]
	v_add_f32_e32 v27, 1.0, v27
	v_div_scale_f32 v34, s[2:3], v19, v25, v19
	v_fmac_f32_e32 v37, v39, v37
	v_div_fmas_f32 v21, v21, v36, v29
	v_mul_f32_e32 v30, v34, v37
	v_div_fixup_f32 v55, v21, v24, v18
	v_div_scale_f32 v18, s[0:1], v27, v27, v20
	v_fma_f32 v26, -v33, v30, v34
	v_rcp_f32_e32 v21, v18
	v_fmac_f32_e32 v30, v26, v37
	v_fma_f32 v26, -v33, v30, v34
	s_mov_b64 vcc, s[2:3]
	v_div_fmas_f32 v24, v26, v37, v30
	v_div_fixup_f32 v56, v24, v25, v19
	v_fma_f32 v19, -v18, v21, 1.0
	v_fmac_f32_e32 v21, v19, v21
	v_div_scale_f32 v19, vcc, v20, v27, v20
	v_mul_f32_e32 v24, v19, v21
	v_fma_f32 v25, -v18, v24, v19
	v_fmac_f32_e32 v24, v25, v21
	v_fma_f32 v18, -v18, v24, v19
	v_div_fmas_f32 v18, v18, v21, v24
	v_div_fixup_f32 v57, v18, v27, v20
